# norm/a_low row loops: LDS reads software-pipelined with counted lgkmcnt waits; gemm1 epilogue stores sc1
# speedup vs baseline: 1.0209x; 1.0209x over previous
; #define LAS __attribute__((address_space(3)))
; __device__ __forceinline__ unsigned cvt_pk_bf16(float lo, float hi) { unsigned r; asm volatile("v_cvt_pk_bf16_f32 %0, %1, %2" : "=v"(r) : "v"(lo), "v"(hi)); return r; }
; __device__ void phase_norm_alow(const Params& P, int l, int half, LAS unsigned char* lds) {
;     ...
;         for (int i = 0; i < 4; ++i) { v[i] = nv[i]; ss += v[i][0] * v[i][0] + v[i][1] * v[i][1] + v[i][2] * v[i][2] + v[i][3] * v[i][3]; }
;         if (row + rstride < TH) {
; #pragma unroll
;             for (int i = 0; i < 4; ++i) nv[i] = *(const f32x4*)(xs + (size_t)(row + rstride) * DM + i * 256 + lane * 4);
;         }
;         ss = wave_sum(ss);
;         const float r = rsqrtf(ss * (1.0f / DM) + EPS);
;         float a[16];
; #pragma unroll
;         for (int c = 0; c < 16; ++c) a[c] = 0.f;
; #pragma unroll
;         for (int i = 0; i < 4; ++i) { f32x4 h = v[i] * r * gv[i];
;             u32x2 w; w.x = cvt_pk_bf16(h[0], h[1]); w.y = cvt_pk_bf16(h[2], h[3]);
;             *(u32x2*)(H + (size_t)row * DM + i * 256 + lane * 4) = w;
; #pragma unroll
;             for (int c = 0; c < 16; ++c) { const f32x4 wv = *(const LAS f32x4*)(WaT + c * 1024 + i * 256 + lane * 4); a[c] += h[0] * wv[0] + h[1] * wv[1] + h[2] * wv[2] + h[3] * wv[3]; } }
.LBB0_120:
	s_or_b64 exec, exec, s[30:31]
	v_mul_f32_e32 v51, v47, v47
	v_mul_f32_e32 v58, v43, v43
	v_fmac_f32_e32 v51, v46, v46
	v_fmac_f32_e32 v58, v42, v42
	v_fmac_f32_e32 v51, v48, v48
	v_fmac_f32_e32 v58, v44, v44
	v_fmac_f32_e32 v51, v49, v49
	v_fmac_f32_e32 v58, v45, v45
	v_add_f32_e32 v51, v51, v58
	v_mul_f32_e32 v58, v39, v39
	v_fmac_f32_e32 v58, v38, v38
	v_fmac_f32_e32 v58, v40, v40
	v_fmac_f32_e32 v58, v41, v41
	v_add_f32_e32 v51, v51, v58
	v_mul_f32_e32 v58, v35, v35
	v_fmac_f32_e32 v58, v34, v34
	v_fmac_f32_e32 v58, v36, v36
	v_fmac_f32_e32 v58, v37, v37
	v_add_f32_e32 v51, v51, v58
	ds_bpermute_b32 v58, v59, v51
	v_lshl_add_u64 v[68:69], s[74:75], 0, v[56:57]
	s_waitcnt lgkmcnt(0)
	v_add_f32_e32 v51, v51, v58
	ds_bpermute_b32 v58, v62, v51
	s_waitcnt lgkmcnt(0)
	v_add_f32_e32 v51, v51, v58
	ds_bpermute_b32 v58, v63, v51
	s_waitcnt lgkmcnt(0)
	v_add_f32_e32 v51, v51, v58
	ds_bpermute_b32 v58, v64, v51
	s_waitcnt lgkmcnt(0)
	v_add_f32_e32 v51, v51, v58
	ds_bpermute_b32 v58, v65, v51
	s_waitcnt lgkmcnt(0)
	v_add_f32_e32 v51, v51, v58
	ds_bpermute_b32 v58, v66, v51
	s_waitcnt lgkmcnt(0)
	v_add_f32_e32 v51, v51, v58
	v_fmamk_f32 v51, v51, 0x3a800000, v1
	v_cmp_gt_f32_e64 s[0:1], s33, v51
	v_mul_f32_e32 v58, 0x4b800000, v51
	s_nop 0
	v_cndmask_b32_e64 v51, v51, v58, s[0:1]
	v_rsq_f32_e32 v51, v51
	s_nop 0
	v_mul_f32_e32 v58, 0x45800000, v51
	v_cndmask_b32_e64 v58, v51, v58, s[0:1]
	v_pk_mul_f32 v[46:47], v[46:47], v[58:59] op_sel_hi:[1,0]
	s_mov_b32 s0, 0x5a88000
	v_pk_mul_f32 v[48:49], v[48:49], v[58:59] op_sel_hi:[1,0]
	v_pk_mul_f32 v[60:61], v[14:15], v[46:47]
	v_add_co_u32_e64 v46, s[0:1], s0, v68
	v_pk_mul_f32 v[48:49], v[16:17], v[48:49]
	v_cvt_pk_bf16_f32 v70, v60, v61
	s_nop 0
	v_addc_co_u32_e64 v47, s[0:1], 0, v69, s[0:1]
	v_cvt_pk_bf16_f32 v71, v48, v49
	global_store_dwordx2 v[46:47], v[70:71], off
	ds_read_b128 v[100:103], v67
	ds_read_b128 v[104:107], v67 offset:4096
	ds_read_b128 v[108:111], v67 offset:8192
	ds_read_b128 v[112:115], v67 offset:12288
	ds_read_b128 v[116:119], v67 offset:16384
	ds_read_b128 v[120:123], v67 offset:20480
	ds_read_b128 v[124:127], v67 offset:24576
	s_waitcnt lgkmcnt(6)
	v_mul_f32_e32 v51, v101, v61
	v_fmac_f32_e32 v51, v100, v60
	v_fmac_f32_e32 v51, v102, v48
	v_fmac_f32_e32 v51, v103, v49
	ds_read_b128 v[128:131], v67 offset:28672
	v_add_f32_e32 v69, 0, v51
	s_waitcnt lgkmcnt(6)
	v_mul_f32_e32 v51, v105, v61
	v_fmac_f32_e32 v51, v104, v60
	v_fmac_f32_e32 v51, v106, v48
	v_fmac_f32_e32 v51, v107, v49
	ds_read_b128 v[100:103], v67 offset:32768
	v_add_f32_e32 v51, 0, v51
	s_waitcnt lgkmcnt(6)
	v_mul_f32_e32 v68, v109, v61
	v_fmac_f32_e32 v68, v108, v60
	v_fmac_f32_e32 v68, v110, v48
	v_fmac_f32_e32 v68, v111, v49
	ds_read_b128 v[104:107], v67 offset:36864
	v_add_f32_e32 v68, 0, v68
	s_waitcnt lgkmcnt(6)
	v_mul_f32_e32 v71, v113, v61
	v_fmac_f32_e32 v71, v112, v60
	v_fmac_f32_e32 v71, v114, v48
	v_fmac_f32_e32 v71, v115, v49
	ds_read_b128 v[108:111], v67 offset:40960
	v_add_f32_e32 v70, 0, v71
	s_waitcnt lgkmcnt(6)
	v_mul_f32_e32 v71, v117, v61
	v_fmac_f32_e32 v71, v116, v60
	v_fmac_f32_e32 v71, v118, v48
	v_fmac_f32_e32 v71, v119, v49
	ds_read_b128 v[112:115], v67 offset:45056
	v_add_f32_e32 v71, 0, v71
	s_waitcnt lgkmcnt(6)
	v_mul_f32_e32 v73, v121, v61
	v_fmac_f32_e32 v73, v120, v60
	v_fmac_f32_e32 v73, v122, v48
	v_fmac_f32_e32 v73, v123, v49
	ds_read_b128 v[116:119], v67 offset:49152
	v_add_f32_e32 v72, 0, v73
	s_waitcnt lgkmcnt(6)
	v_mul_f32_e32 v73, v125, v61
	v_fmac_f32_e32 v73, v124, v60
	v_fmac_f32_e32 v73, v126, v48
	v_fmac_f32_e32 v73, v127, v49
	ds_read_b128 v[120:123], v67 offset:53248
	v_add_f32_e32 v73, 0, v73
	s_waitcnt lgkmcnt(6)
	v_mul_f32_e32 v75, v129, v61
	v_fmac_f32_e32 v75, v128, v60
	v_fmac_f32_e32 v75, v130, v48
	v_fmac_f32_e32 v75, v131, v49
	ds_read_b128 v[124:127], v67 offset:57344
	v_add_f32_e32 v74, 0, v75
	s_waitcnt lgkmcnt(6)
	v_mul_f32_e32 v75, v101, v61
	v_fmac_f32_e32 v75, v100, v60
	v_fmac_f32_e32 v75, v102, v48
	v_fmac_f32_e32 v75, v103, v49
	ds_read_b128 v[128:131], v67 offset:61440
	v_add_f32_e32 v75, 0, v75
	s_waitcnt lgkmcnt(6)
	v_mul_f32_e32 v77, v61, v105
	v_fmac_f32_e32 v77, v60, v104
	v_fmac_f32_e32 v77, v48, v106
	v_fmac_f32_e32 v77, v49, v107
	ds_read_b128 v[100:103], v67 offset:1024
	v_add_f32_e32 v76, 0, v77
	s_waitcnt lgkmcnt(6)
	v_mul_f32_e32 v77, v61, v109
	v_fmac_f32_e32 v77, v60, v108
	v_fmac_f32_e32 v77, v48, v110
	v_fmac_f32_e32 v77, v49, v111
	ds_read_b128 v[104:107], v67 offset:5120
	v_add_f32_e32 v77, 0, v77
	s_waitcnt lgkmcnt(6)
	v_mul_f32_e32 v79, v61, v113
	v_fmac_f32_e32 v79, v60, v112
	v_fmac_f32_e32 v79, v48, v114
	v_fmac_f32_e32 v79, v49, v115
	ds_read_b128 v[108:111], v67 offset:9216
	v_add_f32_e32 v78, 0, v79
	s_waitcnt lgkmcnt(6)
	v_mul_f32_e32 v79, v61, v117
	v_fmac_f32_e32 v79, v60, v116
	v_fmac_f32_e32 v79, v48, v118
	v_fmac_f32_e32 v79, v49, v119
	ds_read_b128 v[112:115], v67 offset:13312
	v_add_f32_e32 v79, 0, v79
	s_waitcnt lgkmcnt(6)
	v_mul_f32_e32 v81, v61, v121
	v_fmac_f32_e32 v81, v60, v120
	v_fmac_f32_e32 v81, v48, v122
	v_fmac_f32_e32 v81, v49, v123
	ds_read_b128 v[116:119], v67 offset:17408
	v_add_f32_e32 v80, 0, v81
	s_waitcnt lgkmcnt(6)
	v_mul_f32_e32 v81, v61, v125
	v_fmac_f32_e32 v81, v60, v124
	v_fmac_f32_e32 v81, v48, v126
	v_fmac_f32_e32 v81, v49, v127
	ds_read_b128 v[120:123], v67 offset:21504
	v_add_f32_e32 v81, 0, v81
	s_waitcnt lgkmcnt(6)
; #define LAS __attribute__((address_space(3)))
; __device__ __forceinline__ unsigned cvt_pk_bf16(float lo, float hi) { unsigned r; asm volatile("v_cvt_pk_bf16_f32 %0, %1, %2" : "=v"(r) : "v"(lo), "v"(hi)); return r; }
; __device__ void phase_norm_alow(const Params& P, int l, int half, LAS unsigned char* lds) {
;     ...
;         for (int i = 0; i < 4; ++i) { f32x4 h = v[i] * r * gv[i];
;             u32x2 w; w.x = cvt_pk_bf16(h[0], h[1]); w.y = cvt_pk_bf16(h[2], h[3]);
;             *(u32x2*)(H + (size_t)row * DM + i * 256 + lane * 4) = w;
; #pragma unroll
;             for (int c = 0; c < 16; ++c) { const f32x4 wv = *(const LAS f32x4*)(WaT + c * 1024 + i * 256 + lane * 4); a[c] += h[0] * wv[0] + h[1] * wv[1] + h[2] * wv[2] + h[3] * wv[3]; } }
	v_mul_f32_e32 v61, v61, v129
	v_fmac_f32_e32 v61, v60, v128
	v_fmac_f32_e32 v61, v48, v130
	v_fmac_f32_e32 v61, v49, v131
	v_add_f32_e32 v48, 0, v61
	v_pk_mul_f32 v[60:61], v[42:43], v[58:59] op_sel_hi:[1,0]
	v_pk_mul_f32 v[42:43], v[44:45], v[58:59] op_sel_hi:[1,0]
	v_pk_mul_f32 v[44:45], v[10:11], v[60:61]
	v_pk_mul_f32 v[42:43], v[12:13], v[42:43]
	v_cvt_pk_bf16_f32 v60, v44, v45
	s_nop 0
	v_cvt_pk_bf16_f32 v61, v42, v43
	ds_read_b128 v[124:127], v67 offset:25600
	global_store_dwordx2 v[46:47], v[60:61], off offset:512
	s_waitcnt lgkmcnt(6)
	v_mul_f32_e32 v49, v45, v101
	v_fmac_f32_e32 v49, v44, v100
	v_fmac_f32_e32 v49, v42, v102
	v_fmac_f32_e32 v49, v43, v103
	ds_read_b128 v[128:131], v67 offset:29696
	v_add_f32_e32 v49, v69, v49
	s_waitcnt lgkmcnt(6)
	v_mul_f32_e32 v60, v45, v105
	v_fmac_f32_e32 v60, v44, v104
	v_fmac_f32_e32 v60, v42, v106
	v_fmac_f32_e32 v60, v43, v107
	ds_read_b128 v[100:103], v67 offset:33792
	v_add_f32_e32 v51, v51, v60
	s_waitcnt lgkmcnt(6)
	v_mul_f32_e32 v60, v45, v109
	v_fmac_f32_e32 v60, v44, v108
	v_fmac_f32_e32 v60, v42, v110
	v_fmac_f32_e32 v60, v43, v111
	ds_read_b128 v[104:107], v67 offset:37888
	v_add_f32_e32 v60, v68, v60
	s_waitcnt lgkmcnt(6)
	v_mul_f32_e32 v61, v45, v113
	v_fmac_f32_e32 v61, v44, v112
	v_fmac_f32_e32 v61, v42, v114
	v_fmac_f32_e32 v61, v43, v115
	ds_read_b128 v[108:111], v67 offset:41984
	v_add_f32_e32 v61, v70, v61
	s_waitcnt lgkmcnt(6)
	v_mul_f32_e32 v68, v45, v117
	v_fmac_f32_e32 v68, v44, v116
	v_fmac_f32_e32 v68, v42, v118
	v_fmac_f32_e32 v68, v43, v119
	ds_read_b128 v[112:115], v67 offset:46080
	v_add_f32_e32 v68, v71, v68
	s_waitcnt lgkmcnt(6)
	v_mul_f32_e32 v69, v45, v121
	v_fmac_f32_e32 v69, v44, v120
	v_fmac_f32_e32 v69, v42, v122
	v_fmac_f32_e32 v69, v43, v123
	ds_read_b128 v[116:119], v67 offset:50176
	v_add_f32_e32 v69, v72, v69
	s_waitcnt lgkmcnt(6)
	v_mul_f32_e32 v70, v45, v125
	v_fmac_f32_e32 v70, v44, v124
	v_fmac_f32_e32 v70, v42, v126
	v_fmac_f32_e32 v70, v43, v127
	ds_read_b128 v[120:123], v67 offset:54272
	v_add_f32_e32 v70, v73, v70
	s_waitcnt lgkmcnt(6)
	v_mul_f32_e32 v71, v45, v129
	v_fmac_f32_e32 v71, v44, v128
	v_fmac_f32_e32 v71, v42, v130
	v_fmac_f32_e32 v71, v43, v131
	ds_read_b128 v[124:127], v67 offset:58368
	v_add_f32_e32 v71, v74, v71
	s_waitcnt lgkmcnt(6)
	v_mul_f32_e32 v72, v45, v101
	v_fmac_f32_e32 v72, v44, v100
	v_fmac_f32_e32 v72, v42, v102
	v_fmac_f32_e32 v72, v43, v103
	ds_read_b128 v[128:131], v67 offset:62464
	v_add_f32_e32 v72, v75, v72
	s_waitcnt lgkmcnt(6)
	v_mul_f32_e32 v73, v45, v105
	v_fmac_f32_e32 v73, v44, v104
	v_fmac_f32_e32 v73, v42, v106
	v_fmac_f32_e32 v73, v43, v107
	ds_read_b128 v[100:103], v67 offset:2048
	v_add_f32_e32 v73, v76, v73
	s_waitcnt lgkmcnt(6)
	v_mul_f32_e32 v74, v45, v109
	v_fmac_f32_e32 v74, v44, v108
	v_fmac_f32_e32 v74, v42, v110
	v_fmac_f32_e32 v74, v43, v111
	ds_read_b128 v[104:107], v67 offset:6144
	v_add_f32_e32 v74, v77, v74
	s_waitcnt lgkmcnt(6)
	v_mul_f32_e32 v75, v45, v113
	v_fmac_f32_e32 v75, v44, v112
	v_fmac_f32_e32 v75, v42, v114
	v_fmac_f32_e32 v75, v43, v115
	ds_read_b128 v[108:111], v67 offset:10240
	v_add_f32_e32 v75, v78, v75
	s_waitcnt lgkmcnt(6)
	v_mul_f32_e32 v76, v45, v117
	v_fmac_f32_e32 v76, v44, v116
	v_fmac_f32_e32 v76, v42, v118
	v_fmac_f32_e32 v76, v43, v119
	ds_read_b128 v[112:115], v67 offset:14336
	v_add_f32_e32 v76, v79, v76
	s_waitcnt lgkmcnt(6)
	v_mul_f32_e32 v77, v45, v121
	v_fmac_f32_e32 v77, v44, v120
	v_fmac_f32_e32 v77, v42, v122
	v_fmac_f32_e32 v77, v43, v123
	ds_read_b128 v[116:119], v67 offset:18432
	v_add_f32_e32 v77, v80, v77
	s_waitcnt lgkmcnt(6)
	v_mul_f32_e32 v78, v45, v125
	v_fmac_f32_e32 v78, v44, v124
	v_fmac_f32_e32 v78, v42, v126
	v_fmac_f32_e32 v78, v43, v127
	v_add_f32_e32 v78, v81, v78
	ds_read_b128 v[120:123], v67 offset:22528
	s_waitcnt lgkmcnt(6)
	v_mul_f32_e32 v45, v45, v129
	v_fmac_f32_e32 v45, v44, v128
	v_fmac_f32_e32 v45, v42, v130
	v_fmac_f32_e32 v45, v43, v131
	v_pk_mul_f32 v[42:43], v[38:39], v[58:59] op_sel_hi:[1,0]
	v_pk_mul_f32 v[38:39], v[40:41], v[58:59] op_sel_hi:[1,0]
	v_pk_mul_f32 v[40:41], v[6:7], v[42:43]
	v_pk_mul_f32 v[38:39], v[8:9], v[38:39]
	v_cvt_pk_bf16_f32 v42, v40, v41
	v_add_f32_e32 v79, v48, v45
	v_cvt_pk_bf16_f32 v43, v38, v39
	global_store_dwordx2 v[46:47], v[42:43], off offset:1024
	ds_read_b128 v[124:127], v67 offset:26624
	ds_read_b128 v[128:131], v67 offset:30720
	s_waitcnt lgkmcnt(7)
	v_mul_f32_e32 v43, v41, v101
	v_fmac_f32_e32 v43, v40, v100
	v_fmac_f32_e32 v43, v38, v102
	v_fmac_f32_e32 v43, v39, v103
	v_add_f32_e32 v42, v49, v43
	s_waitcnt lgkmcnt(6)
	v_mul_f32_e32 v43, v41, v105
	v_fmac_f32_e32 v43, v40, v104
	v_fmac_f32_e32 v43, v38, v106
	v_fmac_f32_e32 v43, v39, v107
	ds_read_b128 v[100:103], v67 offset:34816
	v_add_f32_e32 v43, v51, v43
	s_waitcnt lgkmcnt(6)
	v_mul_f32_e32 v44, v41, v109
	v_fmac_f32_e32 v44, v40, v108
	v_fmac_f32_e32 v44, v38, v110
	v_fmac_f32_e32 v44, v39, v111
	ds_read_b128 v[104:107], v67 offset:38912
	v_add_f32_e32 v44, v60, v44
	s_waitcnt lgkmcnt(6)
	v_mul_f32_e32 v45, v41, v113
	v_fmac_f32_e32 v45, v40, v112
	v_fmac_f32_e32 v45, v38, v114
	v_fmac_f32_e32 v45, v39, v115
	ds_read_b128 v[108:111], v67 offset:43008
	v_add_f32_e32 v45, v61, v45
	s_waitcnt lgkmcnt(6)
	v_mul_f32_e32 v48, v41, v117
	v_fmac_f32_e32 v48, v40, v116
	v_fmac_f32_e32 v48, v38, v118
	v_fmac_f32_e32 v48, v39, v119
	ds_read_b128 v[112:115], v67 offset:47104
	v_add_f32_e32 v48, v68, v48
	s_waitcnt lgkmcnt(6)
	v_mul_f32_e32 v49, v41, v121
	v_fmac_f32_e32 v49, v40, v120
	v_fmac_f32_e32 v49, v38, v122
	v_fmac_f32_e32 v49, v39, v123
	ds_read_b128 v[116:119], v67 offset:51200
	v_add_f32_e32 v49, v69, v49
	s_waitcnt lgkmcnt(6)
; #define LAS __attribute__((address_space(3)))
; __device__ __forceinline__ unsigned cvt_pk_bf16(float lo, float hi) { unsigned r; asm volatile("v_cvt_pk_bf16_f32 %0, %1, %2" : "=v"(r) : "v"(lo), "v"(hi)); return r; }
; __device__ void phase_norm_alow(const Params& P, int l, int half, LAS unsigned char* lds) {
;     ...
;         for (int i = 0; i < 4; ++i) { f32x4 h = v[i] * r * gv[i];
;             u32x2 w; w.x = cvt_pk_bf16(h[0], h[1]); w.y = cvt_pk_bf16(h[2], h[3]);
;             *(u32x2*)(H + (size_t)row * DM + i * 256 + lane * 4) = w;
; #pragma unroll
;             for (int c = 0; c < 16; ++c) { const f32x4 wv = *(const LAS f32x4*)(WaT + c * 1024 + i * 256 + lane * 4); a[c] += h[0] * wv[0] + h[1] * wv[1] + h[2] * wv[2] + h[3] * wv[3]; } }
	v_mul_f32_e32 v51, v41, v125
	v_fmac_f32_e32 v51, v40, v124
	v_fmac_f32_e32 v51, v38, v126
	v_fmac_f32_e32 v51, v39, v127
	ds_read_b128 v[120:123], v67 offset:55296
	v_add_f32_e32 v51, v70, v51
	s_waitcnt lgkmcnt(6)
	v_mul_f32_e32 v60, v41, v129
	v_fmac_f32_e32 v60, v40, v128
	v_fmac_f32_e32 v60, v38, v130
	v_fmac_f32_e32 v60, v39, v131
	v_add_f32_e32 v60, v71, v60
	ds_read_b128 v[124:127], v67 offset:59392
	s_waitcnt lgkmcnt(6)
	v_mul_f32_e32 v61, v41, v101
	v_fmac_f32_e32 v61, v40, v100
	v_fmac_f32_e32 v61, v38, v102
	v_fmac_f32_e32 v61, v39, v103
	ds_read_b128 v[128:131], v67 offset:63488
	v_add_f32_e32 v61, v72, v61
	s_waitcnt lgkmcnt(6)
	v_mul_f32_e32 v69, v41, v105
	v_fmac_f32_e32 v69, v40, v104
	v_fmac_f32_e32 v69, v38, v106
	v_fmac_f32_e32 v69, v39, v107
	v_add_f32_e32 v68, v73, v69
	ds_read_b128 v[100:103], v67 offset:3072
	s_waitcnt lgkmcnt(6)
	v_mul_f32_e32 v69, v41, v109
	v_fmac_f32_e32 v69, v40, v108
	v_fmac_f32_e32 v69, v38, v110
	v_fmac_f32_e32 v69, v39, v111
	ds_read_b128 v[104:107], v67 offset:7168
	v_add_f32_e32 v69, v74, v69
	s_waitcnt lgkmcnt(6)
	v_mul_f32_e32 v71, v41, v113
	v_fmac_f32_e32 v71, v40, v112
	v_fmac_f32_e32 v71, v38, v114
	v_fmac_f32_e32 v71, v39, v115
	v_add_f32_e32 v70, v75, v71
	ds_read_b128 v[108:111], v67 offset:11264
	s_waitcnt lgkmcnt(6)
	v_mul_f32_e32 v71, v41, v117
	v_fmac_f32_e32 v71, v40, v116
	v_fmac_f32_e32 v71, v38, v118
	v_fmac_f32_e32 v71, v39, v119
	ds_read_b128 v[112:115], v67 offset:15360
	v_add_f32_e32 v71, v76, v71
	s_waitcnt lgkmcnt(6)
	v_mul_f32_e32 v73, v41, v121
	v_fmac_f32_e32 v73, v40, v120
	v_fmac_f32_e32 v73, v38, v122
	v_fmac_f32_e32 v73, v39, v123
	v_add_f32_e32 v72, v77, v73
	ds_read_b128 v[116:119], v67 offset:19456
	s_waitcnt lgkmcnt(6)
	v_mul_f32_e32 v73, v41, v125
	v_fmac_f32_e32 v73, v40, v124
	v_fmac_f32_e32 v73, v38, v126
	v_fmac_f32_e32 v73, v39, v127
	ds_read_b128 v[120:123], v67 offset:23552
	v_add_f32_e32 v73, v78, v73
	s_waitcnt lgkmcnt(6)
	v_mul_f32_e32 v41, v41, v129
	v_fmac_f32_e32 v41, v40, v128
	v_fmac_f32_e32 v41, v38, v130
	v_fmac_f32_e32 v41, v39, v131
	v_add_f32_e32 v38, v79, v41
	v_pk_mul_f32 v[40:41], v[34:35], v[58:59] op_sel_hi:[1,0]
	v_pk_mul_f32 v[34:35], v[36:37], v[58:59] op_sel_hi:[1,0]
	v_pk_mul_f32 v[36:37], v[2:3], v[40:41]
	v_pk_mul_f32 v[34:35], v[4:5], v[34:35]
	v_cvt_pk_bf16_f32 v40, v36, v37
	s_nop 0
	v_cvt_pk_bf16_f32 v41, v34, v35
	ds_read_b128 v[124:127], v67 offset:27648
	global_store_dwordx2 v[46:47], v[40:41], off offset:1536
	s_waitcnt lgkmcnt(6)
	v_mul_f32_e32 v39, v37, v101
	v_fmac_f32_e32 v39, v36, v100
	v_fmac_f32_e32 v39, v34, v102
	v_fmac_f32_e32 v39, v35, v103
	ds_read_b128 v[128:131], v67 offset:31744
	v_add_f32_e32 v39, v42, v39
	s_waitcnt lgkmcnt(6)
	v_mul_f32_e32 v40, v37, v105
	v_fmac_f32_e32 v40, v36, v104
	v_fmac_f32_e32 v40, v34, v106
	v_fmac_f32_e32 v40, v35, v107
	ds_read_b128 v[100:103], v67 offset:35840
	v_add_f32_e32 v40, v43, v40
	s_waitcnt lgkmcnt(6)
	v_mul_f32_e32 v41, v37, v109
	v_fmac_f32_e32 v41, v36, v108
	v_fmac_f32_e32 v41, v34, v110
	v_fmac_f32_e32 v41, v35, v111
	ds_read_b128 v[104:107], v67 offset:39936
	v_add_f32_e32 v41, v44, v41
	s_waitcnt lgkmcnt(6)
	v_mul_f32_e32 v42, v37, v113
	v_fmac_f32_e32 v42, v36, v112
	v_fmac_f32_e32 v42, v34, v114
	v_fmac_f32_e32 v42, v35, v115
	v_add_f32_e32 v42, v45, v42
	ds_read_b128 v[108:111], v67 offset:44032
	s_waitcnt lgkmcnt(6)
	v_mul_f32_e32 v43, v37, v117
	v_fmac_f32_e32 v43, v36, v116
	v_fmac_f32_e32 v43, v34, v118
	v_fmac_f32_e32 v43, v35, v119
	ds_read_b128 v[112:115], v67 offset:48128
	v_add_f32_e32 v43, v48, v43
	s_waitcnt lgkmcnt(6)
	v_mul_f32_e32 v45, v37, v121
	v_fmac_f32_e32 v45, v36, v120
	v_fmac_f32_e32 v45, v34, v122
	v_fmac_f32_e32 v45, v35, v123
	v_add_f32_e32 v48, v49, v45
	ds_read_b128 v[116:119], v67 offset:52224
	s_waitcnt lgkmcnt(6)
	v_mul_f32_e32 v45, v37, v125
	v_fmac_f32_e32 v45, v36, v124
	v_fmac_f32_e32 v45, v34, v126
	v_fmac_f32_e32 v45, v35, v127
	v_add_f32_e32 v49, v51, v45
	ds_read_b128 v[120:123], v67 offset:56320
	s_waitcnt lgkmcnt(6)
	v_mul_f32_e32 v45, v37, v129
	v_fmac_f32_e32 v45, v36, v128
	v_fmac_f32_e32 v45, v34, v130
	v_fmac_f32_e32 v45, v35, v131
	v_add_f32_e32 v51, v60, v45
	ds_read_b128 v[124:127], v67 offset:60416
	s_waitcnt lgkmcnt(6)
; #define LAS __attribute__((address_space(3)))
; __device__ __forceinline__ unsigned cvt_pk_bf16(float lo, float hi) { unsigned r; asm volatile("v_cvt_pk_bf16_f32 %0, %1, %2" : "=v"(r) : "v"(lo), "v"(hi)); return r; }
; __device__ void phase_norm_alow(const Params& P, int l, int half, LAS unsigned char* lds) {
;     ...
;         for (int i = 0; i < 4; ++i) { f32x4 h = v[i] * r * gv[i];
;             u32x2 w; w.x = cvt_pk_bf16(h[0], h[1]); w.y = cvt_pk_bf16(h[2], h[3]);
;             *(u32x2*)(H + (size_t)row * DM + i * 256 + lane * 4) = w;
; #pragma unroll
;             for (int c = 0; c < 16; ++c) { const f32x4 wv = *(const LAS f32x4*)(WaT + c * 1024 + i * 256 + lane * 4); a[c] += h[0] * wv[0] + h[1] * wv[1] + h[2] * wv[2] + h[3] * wv[3]; } }
;         float b8[8], b4[4], b2[2], b1;
;         { const bool up = (lane & 32) != 0;
; #pragma unroll
;           for (int c = 0; c < 8; ++c) { const float keep = up ? a[c + 8] : a[c], send = up ? a[c] : a[c + 8]; b8[c] = keep + __shfl_xor(send, 32); } }
;         { const bool up = (lane & 16) != 0;
; #pragma unroll
;           for (int c = 0; c < 4; ++c) { const float keep = up ? b8[c + 4] : b8[c], send = up ? b8[c] : b8[c + 4]; b4[c] = keep + __shfl_xor(send, 16); } }
;         { const bool up = (lane & 8) != 0;
; #pragma unroll
;           for (int c = 0; c < 2; ++c) { const float keep = up ? b4[c + 2] : b4[c], send = up ? b4[c] : b4[c + 2]; b2[c] = keep + __shfl_xor(send, 8); } }
;         { const bool up = (lane & 4) != 0; const float keep = up ? b2[1] : b2[0], send = up ? b2[0] : b2[1]; b1 = keep + __shfl_xor(send, 4); }
;         b1 += __shfl_xor(b1, 2); b1 += __shfl_xor(b1, 1);
;         if ((lane & 3) == 0) { const int co = ((lane >> 5) & 1) * 8 + ((lane >> 4) & 1) * 4 + ((lane >> 3) & 1) * 2 + ((lane >> 2) & 1); AL[(size_t)row * 16 + co] = b1; }
	v_mul_f32_e32 v45, v37, v101
	v_fmac_f32_e32 v45, v36, v100
	v_fmac_f32_e32 v45, v34, v102
	v_fmac_f32_e32 v45, v35, v103
	v_add_f32_e32 v58, v61, v45
	ds_read_b128 v[128:131], v67 offset:64512
	s_waitcnt lgkmcnt(6)
	v_mul_f32_e32 v45, v37, v105
	v_fmac_f32_e32 v45, v36, v104
	v_fmac_f32_e32 v45, v34, v106
	v_fmac_f32_e32 v45, v35, v107
	v_add_f32_e32 v60, v68, v45
	s_waitcnt lgkmcnt(5)
	v_mul_f32_e32 v45, v37, v109
	v_fmac_f32_e32 v45, v36, v108
	v_fmac_f32_e32 v45, v34, v110
	v_fmac_f32_e32 v45, v35, v111
	v_add_f32_e32 v61, v69, v45
	s_waitcnt lgkmcnt(4)
	v_mul_f32_e32 v45, v37, v113
	v_fmac_f32_e32 v45, v36, v112
	v_fmac_f32_e32 v45, v34, v114
	v_fmac_f32_e32 v45, v35, v115
	v_add_f32_e32 v68, v70, v45
	s_waitcnt lgkmcnt(3)
	v_mul_f32_e32 v45, v37, v117
	v_fmac_f32_e32 v45, v36, v116
	v_fmac_f32_e32 v45, v34, v118
	v_fmac_f32_e32 v45, v35, v119
	v_add_f32_e32 v69, v71, v45
	s_waitcnt lgkmcnt(2)
	v_mul_f32_e32 v45, v37, v121
	v_fmac_f32_e32 v45, v36, v120
	v_fmac_f32_e32 v45, v34, v122
	v_fmac_f32_e32 v45, v35, v123
	v_add_f32_e32 v70, v72, v45
	s_waitcnt lgkmcnt(1)
	v_mul_f32_e32 v45, v37, v125
	v_fmac_f32_e32 v45, v36, v124
	v_fmac_f32_e32 v45, v34, v126
	v_fmac_f32_e32 v45, v35, v127
	v_add_f32_e32 v71, v73, v45
	s_waitcnt lgkmcnt(0)
	v_mul_f32_e32 v37, v37, v129
	v_fmac_f32_e32 v37, v36, v128
	v_fmac_f32_e32 v37, v34, v130
	v_fmac_f32_e32 v37, v35, v131
	v_cndmask_b32_e32 v36, v39, v58, vcc
	v_add_f32_e32 v34, v38, v37
	ds_bpermute_b32 v36, v59, v36
	v_cndmask_b32_e32 v37, v40, v60, vcc
	ds_bpermute_b32 v37, v59, v37
	v_cndmask_b32_e32 v38, v41, v61, vcc
	ds_bpermute_b32 v38, v59, v38
	v_cndmask_b32_e32 v35, v58, v39, vcc
	v_cndmask_b32_e32 v39, v42, v68, vcc
	s_waitcnt lgkmcnt(2)
	v_add_f32_e32 v35, v35, v36
	v_cndmask_b32_e32 v36, v60, v40, vcc
	ds_bpermute_b32 v39, v59, v39
	v_cndmask_b32_e32 v40, v43, v69, vcc
	s_waitcnt lgkmcnt(2)
	v_add_f32_e32 v36, v36, v37
	v_cndmask_b32_e32 v37, v61, v41, vcc
	ds_bpermute_b32 v40, v59, v40
	v_cndmask_b32_e32 v41, v48, v70, vcc
	s_waitcnt lgkmcnt(2)
	v_add_f32_e32 v37, v37, v38
	v_cndmask_b32_e32 v38, v68, v42, vcc
	ds_bpermute_b32 v41, v59, v41
	v_cndmask_b32_e32 v42, v49, v71, vcc
	ds_bpermute_b32 v42, v59, v42
	s_waitcnt lgkmcnt(3)
	v_add_f32_e32 v38, v38, v39
	v_cndmask_b32_e32 v39, v69, v43, vcc
	s_waitcnt lgkmcnt(2)
	v_add_f32_e32 v39, v39, v40
	v_cndmask_b32_e32 v40, v70, v48, vcc
	s_waitcnt lgkmcnt(1)
	v_add_f32_e32 v40, v40, v41
	v_cndmask_b32_e32 v41, v71, v49, vcc
	s_waitcnt lgkmcnt(0)
	v_add_f32_e32 v41, v41, v42
	v_cndmask_b32_e32 v42, v34, v51, vcc
	v_cndmask_b32_e32 v34, v51, v34, vcc
	ds_bpermute_b32 v34, v59, v34
	s_waitcnt lgkmcnt(0)
	v_add_f32_e32 v34, v42, v34
	v_cndmask_b32_e64 v42, v39, v35, s[36:37]
	v_cndmask_b32_e64 v35, v35, v39, s[36:37]
	v_cndmask_b32_e64 v39, v40, v36, s[36:37]
	v_cndmask_b32_e64 v36, v36, v40, s[36:37]
	ds_bpermute_b32 v36, v62, v36
	ds_bpermute_b32 v35, v62, v35
	s_waitcnt lgkmcnt(1)
	v_add_f32_e32 v36, v39, v36
	v_cndmask_b32_e64 v39, v41, v37, s[36:37]
	v_cndmask_b32_e64 v37, v37, v41, s[36:37]
	ds_bpermute_b32 v37, v62, v37
	s_waitcnt lgkmcnt(1)
	v_add_f32_e32 v35, v42, v35
	s_waitcnt lgkmcnt(0)
	v_add_f32_e32 v37, v39, v37
	v_cndmask_b32_e64 v39, v34, v38, s[36:37]
	v_cndmask_b32_e64 v34, v38, v34, s[36:37]
	ds_bpermute_b32 v34, v62, v34
	v_cndmask_b32_e64 v38, v37, v35, s[38:39]
	v_cndmask_b32_e64 v35, v35, v37, s[38:39]
	ds_bpermute_b32 v35, v63, v35
	s_waitcnt lgkmcnt(1)
	v_add_f32_e32 v34, v39, v34
	v_cndmask_b32_e64 v37, v34, v36, s[38:39]
	v_cndmask_b32_e64 v34, v36, v34, s[38:39]
	ds_bpermute_b32 v34, v63, v34
	s_waitcnt lgkmcnt(1)
	v_add_f32_e32 v35, v38, v35
	s_waitcnt lgkmcnt(0)
	v_add_f32_e32 v34, v37, v34
	v_cndmask_b32_e64 v36, v34, v35, s[40:41]
	v_cndmask_b32_e64 v34, v35, v34, s[40:41]
	ds_bpermute_b32 v34, v64, v34
	s_waitcnt lgkmcnt(0)
	v_add_f32_e32 v34, v36, v34
	ds_bpermute_b32 v35, v65, v34
	s_waitcnt lgkmcnt(0)
	v_add_f32_e32 v34, v34, v35
	ds_bpermute_b32 v35, v66, v34
	s_and_saveexec_b64 s[0:1], s[42:43]
	s_cbranch_execz .LBB0_117
	v_lshl_add_u64 v[36:37], s[74:75], 0, v[54:55]
	s_waitcnt lgkmcnt(0)
	v_add_f32_e32 v34, v34, v35
	global_store_dword v[36:37], v34, off
	s_branch .LBB0_117

; #define LAS __attribute__((address_space(3)))
; __device__ __forceinline__ unsigned cvt_pk_bf16(float lo, float hi) { unsigned r; asm volatile("v_cvt_pk_bf16_f32 %0, %1, %2" : "=v"(r) : "v"(lo), "v"(hi)); return r; }
; __device__ void phase_norm_alow(const Params& P, int l, int half, LAS unsigned char* lds) {
;     ...
;         for (int i = 0; i < 4; ++i) { v[i] = nv[i]; ss += v[i][0] * v[i][0] + v[i][1] * v[i][1] + v[i][2] * v[i][2] + v[i][3] * v[i][3]; }
;         if (row + rstride < TH) {
; #pragma unroll
;             for (int i = 0; i < 4; ++i) nv[i] = *(const f32x4*)(xs + (size_t)(row + rstride) * DM + i * 256 + lane * 4);
;         }
;         ss = wave_sum(ss);
;         const float r = rsqrtf(ss * (1.0f / DM) + EPS);
;         float a[16];
; #pragma unroll
;         for (int c = 0; c < 16; ++c) a[c] = 0.f;
; #pragma unroll
;         for (int i = 0; i < 4; ++i) { f32x4 h = v[i] * r * gv[i];
;             u32x2 w; w.x = cvt_pk_bf16(h[0], h[1]); w.y = cvt_pk_bf16(h[2], h[3]);
;             *(u32x2*)(H + (size_t)row * DM + i * 256 + lane * 4) = w;
; #pragma unroll
;             for (int c = 0; c < 16; ++c) { const f32x4 wv = *(const LAS f32x4*)(WaT + c * 1024 + i * 256 + lane * 4); a[c] += h[0] * wv[0] + h[1] * wv[1] + h[2] * wv[2] + h[3] * wv[3]; } }
.LBB0_242:
	s_or_b64 exec, exec, s[30:31]
	v_mul_f32_e32 v51, v47, v47
	v_mul_f32_e32 v58, v43, v43
	v_fmac_f32_e32 v51, v46, v46
	v_fmac_f32_e32 v58, v42, v42
	v_fmac_f32_e32 v51, v48, v48
	v_fmac_f32_e32 v58, v44, v44
	v_fmac_f32_e32 v51, v49, v49
	v_fmac_f32_e32 v58, v45, v45
	v_add_f32_e32 v51, v51, v58
	v_mul_f32_e32 v58, v39, v39
	v_fmac_f32_e32 v58, v38, v38
	v_fmac_f32_e32 v58, v40, v40
	v_fmac_f32_e32 v58, v41, v41
	v_add_f32_e32 v51, v51, v58
	v_mul_f32_e32 v58, v35, v35
	v_fmac_f32_e32 v58, v34, v34
	v_fmac_f32_e32 v58, v36, v36
	v_fmac_f32_e32 v58, v37, v37
	v_add_f32_e32 v51, v51, v58
	ds_bpermute_b32 v58, v59, v51
	v_lshl_add_u64 v[68:69], s[74:75], 0, v[54:55]
	s_waitcnt lgkmcnt(0)
	v_add_f32_e32 v51, v51, v58
	ds_bpermute_b32 v58, v62, v51
	s_waitcnt lgkmcnt(0)
	v_add_f32_e32 v51, v51, v58
	ds_bpermute_b32 v58, v63, v51
	s_waitcnt lgkmcnt(0)
	v_add_f32_e32 v51, v51, v58
	ds_bpermute_b32 v58, v64, v51
	s_waitcnt lgkmcnt(0)
	v_add_f32_e32 v51, v51, v58
	ds_bpermute_b32 v58, v65, v51
	s_waitcnt lgkmcnt(0)
	v_add_f32_e32 v51, v51, v58
	ds_bpermute_b32 v58, v66, v51
	s_waitcnt lgkmcnt(0)
	v_add_f32_e32 v51, v51, v58
	v_fmamk_f32 v51, v51, 0x3a800000, v1
	v_cmp_gt_f32_e64 s[0:1], s33, v51
	v_mul_f32_e32 v58, 0x4b800000, v51
	s_nop 0
	v_cndmask_b32_e64 v51, v51, v58, s[0:1]
	v_rsq_f32_e32 v51, v51
	s_nop 0
	v_mul_f32_e32 v58, 0x45800000, v51
	v_cndmask_b32_e64 v58, v51, v58, s[0:1]
	v_pk_mul_f32 v[46:47], v[46:47], v[58:59] op_sel_hi:[1,0]
	s_mov_b32 s0, 0x5a88000
	v_pk_mul_f32 v[48:49], v[48:49], v[58:59] op_sel_hi:[1,0]
	v_pk_mul_f32 v[60:61], v[14:15], v[46:47]
	v_add_co_u32_e64 v46, s[0:1], s0, v68
	v_pk_mul_f32 v[48:49], v[16:17], v[48:49]
	v_cvt_pk_bf16_f32 v70, v60, v61
	s_nop 0
	v_addc_co_u32_e64 v47, s[0:1], 0, v69, s[0:1]
	v_cvt_pk_bf16_f32 v71, v48, v49
	global_store_dwordx2 v[46:47], v[70:71], off
	ds_read_b128 v[100:103], v67
	ds_read_b128 v[104:107], v67 offset:4096
	ds_read_b128 v[108:111], v67 offset:8192
	ds_read_b128 v[112:115], v67 offset:12288
	ds_read_b128 v[116:119], v67 offset:16384
	ds_read_b128 v[120:123], v67 offset:20480
	ds_read_b128 v[124:127], v67 offset:24576
	s_waitcnt lgkmcnt(6)
	v_mul_f32_e32 v51, v101, v61
	v_fmac_f32_e32 v51, v100, v60
	v_fmac_f32_e32 v51, v102, v48
	v_fmac_f32_e32 v51, v103, v49
	ds_read_b128 v[128:131], v67 offset:28672
	v_add_f32_e32 v69, 0, v51
	s_waitcnt lgkmcnt(6)
	v_mul_f32_e32 v51, v105, v61
	v_fmac_f32_e32 v51, v104, v60
	v_fmac_f32_e32 v51, v106, v48
	v_fmac_f32_e32 v51, v107, v49
	ds_read_b128 v[100:103], v67 offset:32768
	v_add_f32_e32 v51, 0, v51
	s_waitcnt lgkmcnt(6)
	v_mul_f32_e32 v68, v109, v61
	v_fmac_f32_e32 v68, v108, v60
	v_fmac_f32_e32 v68, v110, v48
	v_fmac_f32_e32 v68, v111, v49
	ds_read_b128 v[104:107], v67 offset:36864
	v_add_f32_e32 v68, 0, v68
	s_waitcnt lgkmcnt(6)
	v_mul_f32_e32 v71, v113, v61
	v_fmac_f32_e32 v71, v112, v60
	v_fmac_f32_e32 v71, v114, v48
	v_fmac_f32_e32 v71, v115, v49
	ds_read_b128 v[108:111], v67 offset:40960
	v_add_f32_e32 v70, 0, v71
	s_waitcnt lgkmcnt(6)
	v_mul_f32_e32 v71, v117, v61
	v_fmac_f32_e32 v71, v116, v60
	v_fmac_f32_e32 v71, v118, v48
	v_fmac_f32_e32 v71, v119, v49
	ds_read_b128 v[112:115], v67 offset:45056
	v_add_f32_e32 v71, 0, v71
	s_waitcnt lgkmcnt(6)
	v_mul_f32_e32 v73, v121, v61
	v_fmac_f32_e32 v73, v120, v60
	v_fmac_f32_e32 v73, v122, v48
	v_fmac_f32_e32 v73, v123, v49
	ds_read_b128 v[116:119], v67 offset:49152
	v_add_f32_e32 v72, 0, v73
	s_waitcnt lgkmcnt(6)
	v_mul_f32_e32 v73, v125, v61
	v_fmac_f32_e32 v73, v124, v60
	v_fmac_f32_e32 v73, v126, v48
	v_fmac_f32_e32 v73, v127, v49
	ds_read_b128 v[120:123], v67 offset:53248
	v_add_f32_e32 v73, 0, v73
	s_waitcnt lgkmcnt(6)
	v_mul_f32_e32 v75, v129, v61
	v_fmac_f32_e32 v75, v128, v60
	v_fmac_f32_e32 v75, v130, v48
	v_fmac_f32_e32 v75, v131, v49
	ds_read_b128 v[124:127], v67 offset:57344
	v_add_f32_e32 v74, 0, v75
	s_waitcnt lgkmcnt(6)
	v_mul_f32_e32 v75, v101, v61
	v_fmac_f32_e32 v75, v100, v60
	v_fmac_f32_e32 v75, v102, v48
	v_fmac_f32_e32 v75, v103, v49
	ds_read_b128 v[128:131], v67 offset:61440
	v_add_f32_e32 v75, 0, v75
	s_waitcnt lgkmcnt(6)
	v_mul_f32_e32 v77, v61, v105
	v_fmac_f32_e32 v77, v60, v104
	v_fmac_f32_e32 v77, v48, v106
	v_fmac_f32_e32 v77, v49, v107
	ds_read_b128 v[100:103], v67 offset:1024
	v_add_f32_e32 v76, 0, v77
	s_waitcnt lgkmcnt(6)
	v_mul_f32_e32 v77, v61, v109
	v_fmac_f32_e32 v77, v60, v108
	v_fmac_f32_e32 v77, v48, v110
	v_fmac_f32_e32 v77, v49, v111
	ds_read_b128 v[104:107], v67 offset:5120
	v_add_f32_e32 v77, 0, v77
	s_waitcnt lgkmcnt(6)
	v_mul_f32_e32 v79, v61, v113
	v_fmac_f32_e32 v79, v60, v112
	v_fmac_f32_e32 v79, v48, v114
	v_fmac_f32_e32 v79, v49, v115
	ds_read_b128 v[108:111], v67 offset:9216
	v_add_f32_e32 v78, 0, v79
	s_waitcnt lgkmcnt(6)
	v_mul_f32_e32 v79, v61, v117
	v_fmac_f32_e32 v79, v60, v116
	v_fmac_f32_e32 v79, v48, v118
	v_fmac_f32_e32 v79, v49, v119
	ds_read_b128 v[112:115], v67 offset:13312
	v_add_f32_e32 v79, 0, v79
	s_waitcnt lgkmcnt(6)
	v_mul_f32_e32 v81, v61, v121
	v_fmac_f32_e32 v81, v60, v120
	v_fmac_f32_e32 v81, v48, v122
	v_fmac_f32_e32 v81, v49, v123
	ds_read_b128 v[116:119], v67 offset:17408
	v_add_f32_e32 v80, 0, v81
	s_waitcnt lgkmcnt(6)
	v_mul_f32_e32 v81, v61, v125
	v_fmac_f32_e32 v81, v60, v124
	v_fmac_f32_e32 v81, v48, v126
	v_fmac_f32_e32 v81, v49, v127
	ds_read_b128 v[120:123], v67 offset:21504
	v_add_f32_e32 v81, 0, v81
	s_waitcnt lgkmcnt(6)
; #define LAS __attribute__((address_space(3)))
; __device__ __forceinline__ unsigned cvt_pk_bf16(float lo, float hi) { unsigned r; asm volatile("v_cvt_pk_bf16_f32 %0, %1, %2" : "=v"(r) : "v"(lo), "v"(hi)); return r; }
; __device__ void phase_norm_alow(const Params& P, int l, int half, LAS unsigned char* lds) {
;     ...
;         for (int i = 0; i < 4; ++i) { f32x4 h = v[i] * r * gv[i];
;             u32x2 w; w.x = cvt_pk_bf16(h[0], h[1]); w.y = cvt_pk_bf16(h[2], h[3]);
;             *(u32x2*)(H + (size_t)row * DM + i * 256 + lane * 4) = w;
; #pragma unroll
;             for (int c = 0; c < 16; ++c) { const f32x4 wv = *(const LAS f32x4*)(WaT + c * 1024 + i * 256 + lane * 4); a[c] += h[0] * wv[0] + h[1] * wv[1] + h[2] * wv[2] + h[3] * wv[3]; } }
	v_mul_f32_e32 v61, v61, v129
	v_fmac_f32_e32 v61, v60, v128
	v_fmac_f32_e32 v61, v48, v130
	v_fmac_f32_e32 v61, v49, v131
	v_add_f32_e32 v48, 0, v61
	v_pk_mul_f32 v[60:61], v[42:43], v[58:59] op_sel_hi:[1,0]
	v_pk_mul_f32 v[42:43], v[44:45], v[58:59] op_sel_hi:[1,0]
	v_pk_mul_f32 v[44:45], v[10:11], v[60:61]
	v_pk_mul_f32 v[42:43], v[12:13], v[42:43]
	v_cvt_pk_bf16_f32 v60, v44, v45
	s_nop 0
	v_cvt_pk_bf16_f32 v61, v42, v43
	ds_read_b128 v[124:127], v67 offset:25600
	global_store_dwordx2 v[46:47], v[60:61], off offset:512
	s_waitcnt lgkmcnt(6)
	v_mul_f32_e32 v49, v45, v101
	v_fmac_f32_e32 v49, v44, v100
	v_fmac_f32_e32 v49, v42, v102
	v_fmac_f32_e32 v49, v43, v103
	ds_read_b128 v[128:131], v67 offset:29696
	v_add_f32_e32 v49, v69, v49
	s_waitcnt lgkmcnt(6)
	v_mul_f32_e32 v60, v45, v105
	v_fmac_f32_e32 v60, v44, v104
	v_fmac_f32_e32 v60, v42, v106
	v_fmac_f32_e32 v60, v43, v107
	ds_read_b128 v[100:103], v67 offset:33792
	v_add_f32_e32 v51, v51, v60
	s_waitcnt lgkmcnt(6)
	v_mul_f32_e32 v60, v45, v109
	v_fmac_f32_e32 v60, v44, v108
	v_fmac_f32_e32 v60, v42, v110
	v_fmac_f32_e32 v60, v43, v111
	ds_read_b128 v[104:107], v67 offset:37888
	v_add_f32_e32 v60, v68, v60
	s_waitcnt lgkmcnt(6)
	v_mul_f32_e32 v61, v45, v113
	v_fmac_f32_e32 v61, v44, v112
	v_fmac_f32_e32 v61, v42, v114
	v_fmac_f32_e32 v61, v43, v115
	ds_read_b128 v[108:111], v67 offset:41984
	v_add_f32_e32 v61, v70, v61
	s_waitcnt lgkmcnt(6)
	v_mul_f32_e32 v68, v45, v117
	v_fmac_f32_e32 v68, v44, v116
	v_fmac_f32_e32 v68, v42, v118
	v_fmac_f32_e32 v68, v43, v119
	ds_read_b128 v[112:115], v67 offset:46080
	v_add_f32_e32 v68, v71, v68
	s_waitcnt lgkmcnt(6)
	v_mul_f32_e32 v69, v45, v121
	v_fmac_f32_e32 v69, v44, v120
	v_fmac_f32_e32 v69, v42, v122
	v_fmac_f32_e32 v69, v43, v123
	ds_read_b128 v[116:119], v67 offset:50176
	v_add_f32_e32 v69, v72, v69
	s_waitcnt lgkmcnt(6)
	v_mul_f32_e32 v70, v45, v125
	v_fmac_f32_e32 v70, v44, v124
	v_fmac_f32_e32 v70, v42, v126
	v_fmac_f32_e32 v70, v43, v127
	ds_read_b128 v[120:123], v67 offset:54272
	v_add_f32_e32 v70, v73, v70
	s_waitcnt lgkmcnt(6)
	v_mul_f32_e32 v71, v45, v129
	v_fmac_f32_e32 v71, v44, v128
	v_fmac_f32_e32 v71, v42, v130
	v_fmac_f32_e32 v71, v43, v131
	ds_read_b128 v[124:127], v67 offset:58368
	v_add_f32_e32 v71, v74, v71
	s_waitcnt lgkmcnt(6)
	v_mul_f32_e32 v72, v45, v101
	v_fmac_f32_e32 v72, v44, v100
	v_fmac_f32_e32 v72, v42, v102
	v_fmac_f32_e32 v72, v43, v103
	ds_read_b128 v[128:131], v67 offset:62464
	v_add_f32_e32 v72, v75, v72
	s_waitcnt lgkmcnt(6)
	v_mul_f32_e32 v73, v45, v105
	v_fmac_f32_e32 v73, v44, v104
	v_fmac_f32_e32 v73, v42, v106
	v_fmac_f32_e32 v73, v43, v107
	ds_read_b128 v[100:103], v67 offset:2048
	v_add_f32_e32 v73, v76, v73
	s_waitcnt lgkmcnt(6)
	v_mul_f32_e32 v74, v45, v109
	v_fmac_f32_e32 v74, v44, v108
	v_fmac_f32_e32 v74, v42, v110
	v_fmac_f32_e32 v74, v43, v111
	ds_read_b128 v[104:107], v67 offset:6144
	v_add_f32_e32 v74, v77, v74
	s_waitcnt lgkmcnt(6)
	v_mul_f32_e32 v75, v45, v113
	v_fmac_f32_e32 v75, v44, v112
	v_fmac_f32_e32 v75, v42, v114
	v_fmac_f32_e32 v75, v43, v115
	ds_read_b128 v[108:111], v67 offset:10240
	v_add_f32_e32 v75, v78, v75
	s_waitcnt lgkmcnt(6)
	v_mul_f32_e32 v76, v45, v117
	v_fmac_f32_e32 v76, v44, v116
	v_fmac_f32_e32 v76, v42, v118
	v_fmac_f32_e32 v76, v43, v119
	ds_read_b128 v[112:115], v67 offset:14336
	v_add_f32_e32 v76, v79, v76
	s_waitcnt lgkmcnt(6)
	v_mul_f32_e32 v77, v45, v121
	v_fmac_f32_e32 v77, v44, v120
	v_fmac_f32_e32 v77, v42, v122
	v_fmac_f32_e32 v77, v43, v123
	ds_read_b128 v[116:119], v67 offset:18432
	v_add_f32_e32 v77, v80, v77
	s_waitcnt lgkmcnt(6)
	v_mul_f32_e32 v78, v45, v125
	v_fmac_f32_e32 v78, v44, v124
	v_fmac_f32_e32 v78, v42, v126
	v_fmac_f32_e32 v78, v43, v127
	v_add_f32_e32 v78, v81, v78
	ds_read_b128 v[120:123], v67 offset:22528
	s_waitcnt lgkmcnt(6)
	v_mul_f32_e32 v45, v45, v129
	v_fmac_f32_e32 v45, v44, v128
	v_fmac_f32_e32 v45, v42, v130
	v_fmac_f32_e32 v45, v43, v131
	v_pk_mul_f32 v[42:43], v[38:39], v[58:59] op_sel_hi:[1,0]
	v_pk_mul_f32 v[38:39], v[40:41], v[58:59] op_sel_hi:[1,0]
	v_pk_mul_f32 v[40:41], v[6:7], v[42:43]
	v_pk_mul_f32 v[38:39], v[8:9], v[38:39]
	v_cvt_pk_bf16_f32 v42, v40, v41
	v_add_f32_e32 v79, v48, v45
	v_cvt_pk_bf16_f32 v43, v38, v39
	global_store_dwordx2 v[46:47], v[42:43], off offset:1024
	ds_read_b128 v[124:127], v67 offset:26624
	ds_read_b128 v[128:131], v67 offset:30720
	s_waitcnt lgkmcnt(7)
	v_mul_f32_e32 v43, v41, v101
	v_fmac_f32_e32 v43, v40, v100
	v_fmac_f32_e32 v43, v38, v102
	v_fmac_f32_e32 v43, v39, v103
	v_add_f32_e32 v42, v49, v43
	s_waitcnt lgkmcnt(6)
	v_mul_f32_e32 v43, v41, v105
	v_fmac_f32_e32 v43, v40, v104
	v_fmac_f32_e32 v43, v38, v106
	v_fmac_f32_e32 v43, v39, v107
	ds_read_b128 v[100:103], v67 offset:34816
	v_add_f32_e32 v43, v51, v43
	s_waitcnt lgkmcnt(6)
	v_mul_f32_e32 v44, v41, v109
	v_fmac_f32_e32 v44, v40, v108
	v_fmac_f32_e32 v44, v38, v110
	v_fmac_f32_e32 v44, v39, v111
	ds_read_b128 v[104:107], v67 offset:38912
	v_add_f32_e32 v44, v60, v44
	s_waitcnt lgkmcnt(6)
	v_mul_f32_e32 v45, v41, v113
	v_fmac_f32_e32 v45, v40, v112
	v_fmac_f32_e32 v45, v38, v114
	v_fmac_f32_e32 v45, v39, v115
	ds_read_b128 v[108:111], v67 offset:43008
	v_add_f32_e32 v45, v61, v45
	s_waitcnt lgkmcnt(6)
	v_mul_f32_e32 v48, v41, v117
	v_fmac_f32_e32 v48, v40, v116
	v_fmac_f32_e32 v48, v38, v118
	v_fmac_f32_e32 v48, v39, v119
	ds_read_b128 v[112:115], v67 offset:47104
	v_add_f32_e32 v48, v68, v48
	s_waitcnt lgkmcnt(6)
	v_mul_f32_e32 v49, v41, v121
	v_fmac_f32_e32 v49, v40, v120
	v_fmac_f32_e32 v49, v38, v122
	v_fmac_f32_e32 v49, v39, v123
	ds_read_b128 v[116:119], v67 offset:51200
	v_add_f32_e32 v49, v69, v49
	s_waitcnt lgkmcnt(6)
; #define LAS __attribute__((address_space(3)))
; __device__ __forceinline__ unsigned cvt_pk_bf16(float lo, float hi) { unsigned r; asm volatile("v_cvt_pk_bf16_f32 %0, %1, %2" : "=v"(r) : "v"(lo), "v"(hi)); return r; }
; __device__ void phase_norm_alow(const Params& P, int l, int half, LAS unsigned char* lds) {
;     ...
;         for (int i = 0; i < 4; ++i) { f32x4 h = v[i] * r * gv[i];
;             u32x2 w; w.x = cvt_pk_bf16(h[0], h[1]); w.y = cvt_pk_bf16(h[2], h[3]);
;             *(u32x2*)(H + (size_t)row * DM + i * 256 + lane * 4) = w;
; #pragma unroll
;             for (int c = 0; c < 16; ++c) { const f32x4 wv = *(const LAS f32x4*)(WaT + c * 1024 + i * 256 + lane * 4); a[c] += h[0] * wv[0] + h[1] * wv[1] + h[2] * wv[2] + h[3] * wv[3]; } }
	v_mul_f32_e32 v51, v41, v125
	v_fmac_f32_e32 v51, v40, v124
	v_fmac_f32_e32 v51, v38, v126
	v_fmac_f32_e32 v51, v39, v127
	ds_read_b128 v[120:123], v67 offset:55296
	v_add_f32_e32 v51, v70, v51
	s_waitcnt lgkmcnt(6)
	v_mul_f32_e32 v60, v41, v129
	v_fmac_f32_e32 v60, v40, v128
	v_fmac_f32_e32 v60, v38, v130
	v_fmac_f32_e32 v60, v39, v131
	v_add_f32_e32 v60, v71, v60
	ds_read_b128 v[124:127], v67 offset:59392
	s_waitcnt lgkmcnt(6)
	v_mul_f32_e32 v61, v41, v101
	v_fmac_f32_e32 v61, v40, v100
	v_fmac_f32_e32 v61, v38, v102
	v_fmac_f32_e32 v61, v39, v103
	ds_read_b128 v[128:131], v67 offset:63488
	v_add_f32_e32 v61, v72, v61
	s_waitcnt lgkmcnt(6)
	v_mul_f32_e32 v69, v41, v105
	v_fmac_f32_e32 v69, v40, v104
	v_fmac_f32_e32 v69, v38, v106
	v_fmac_f32_e32 v69, v39, v107
	v_add_f32_e32 v68, v73, v69
	ds_read_b128 v[100:103], v67 offset:3072
	s_waitcnt lgkmcnt(6)
	v_mul_f32_e32 v69, v41, v109
	v_fmac_f32_e32 v69, v40, v108
	v_fmac_f32_e32 v69, v38, v110
	v_fmac_f32_e32 v69, v39, v111
	ds_read_b128 v[104:107], v67 offset:7168
	v_add_f32_e32 v69, v74, v69
	s_waitcnt lgkmcnt(6)
	v_mul_f32_e32 v71, v41, v113
	v_fmac_f32_e32 v71, v40, v112
	v_fmac_f32_e32 v71, v38, v114
	v_fmac_f32_e32 v71, v39, v115
	v_add_f32_e32 v70, v75, v71
	ds_read_b128 v[108:111], v67 offset:11264
	s_waitcnt lgkmcnt(6)
	v_mul_f32_e32 v71, v41, v117
	v_fmac_f32_e32 v71, v40, v116
	v_fmac_f32_e32 v71, v38, v118
	v_fmac_f32_e32 v71, v39, v119
	ds_read_b128 v[112:115], v67 offset:15360
	v_add_f32_e32 v71, v76, v71
	s_waitcnt lgkmcnt(6)
	v_mul_f32_e32 v73, v41, v121
	v_fmac_f32_e32 v73, v40, v120
	v_fmac_f32_e32 v73, v38, v122
	v_fmac_f32_e32 v73, v39, v123
	v_add_f32_e32 v72, v77, v73
	ds_read_b128 v[116:119], v67 offset:19456
	s_waitcnt lgkmcnt(6)
	v_mul_f32_e32 v73, v41, v125
	v_fmac_f32_e32 v73, v40, v124
	v_fmac_f32_e32 v73, v38, v126
	v_fmac_f32_e32 v73, v39, v127
	ds_read_b128 v[120:123], v67 offset:23552
	v_add_f32_e32 v73, v78, v73
	s_waitcnt lgkmcnt(6)
	v_mul_f32_e32 v41, v41, v129
	v_fmac_f32_e32 v41, v40, v128
	v_fmac_f32_e32 v41, v38, v130
	v_fmac_f32_e32 v41, v39, v131
	v_add_f32_e32 v38, v79, v41
	v_pk_mul_f32 v[40:41], v[34:35], v[58:59] op_sel_hi:[1,0]
	v_pk_mul_f32 v[34:35], v[36:37], v[58:59] op_sel_hi:[1,0]
	v_pk_mul_f32 v[36:37], v[2:3], v[40:41]
	v_pk_mul_f32 v[34:35], v[4:5], v[34:35]
	v_cvt_pk_bf16_f32 v40, v36, v37
	s_nop 0
	v_cvt_pk_bf16_f32 v41, v34, v35
	ds_read_b128 v[124:127], v67 offset:27648
	global_store_dwordx2 v[46:47], v[40:41], off offset:1536
	s_waitcnt lgkmcnt(6)
	v_mul_f32_e32 v39, v37, v101
	v_fmac_f32_e32 v39, v36, v100
	v_fmac_f32_e32 v39, v34, v102
	v_fmac_f32_e32 v39, v35, v103
	ds_read_b128 v[128:131], v67 offset:31744
	v_add_f32_e32 v39, v42, v39
	s_waitcnt lgkmcnt(6)
	v_mul_f32_e32 v40, v37, v105
	v_fmac_f32_e32 v40, v36, v104
	v_fmac_f32_e32 v40, v34, v106
	v_fmac_f32_e32 v40, v35, v107
	ds_read_b128 v[100:103], v67 offset:35840
	v_add_f32_e32 v40, v43, v40
	s_waitcnt lgkmcnt(6)
	v_mul_f32_e32 v41, v37, v109
	v_fmac_f32_e32 v41, v36, v108
	v_fmac_f32_e32 v41, v34, v110
	v_fmac_f32_e32 v41, v35, v111
	ds_read_b128 v[104:107], v67 offset:39936
	v_add_f32_e32 v41, v44, v41
	s_waitcnt lgkmcnt(6)
	v_mul_f32_e32 v42, v37, v113
	v_fmac_f32_e32 v42, v36, v112
	v_fmac_f32_e32 v42, v34, v114
	v_fmac_f32_e32 v42, v35, v115
	v_add_f32_e32 v42, v45, v42
	ds_read_b128 v[108:111], v67 offset:44032
	s_waitcnt lgkmcnt(6)
	v_mul_f32_e32 v43, v37, v117
	v_fmac_f32_e32 v43, v36, v116
	v_fmac_f32_e32 v43, v34, v118
	v_fmac_f32_e32 v43, v35, v119
	ds_read_b128 v[112:115], v67 offset:48128
	v_add_f32_e32 v43, v48, v43
	s_waitcnt lgkmcnt(6)
	v_mul_f32_e32 v45, v37, v121
	v_fmac_f32_e32 v45, v36, v120
	v_fmac_f32_e32 v45, v34, v122
	v_fmac_f32_e32 v45, v35, v123
	v_add_f32_e32 v48, v49, v45
	ds_read_b128 v[116:119], v67 offset:52224
	s_waitcnt lgkmcnt(6)
	v_mul_f32_e32 v45, v37, v125
	v_fmac_f32_e32 v45, v36, v124
	v_fmac_f32_e32 v45, v34, v126
	v_fmac_f32_e32 v45, v35, v127
	v_add_f32_e32 v49, v51, v45
	ds_read_b128 v[120:123], v67 offset:56320
	s_waitcnt lgkmcnt(6)
	v_mul_f32_e32 v45, v37, v129
	v_fmac_f32_e32 v45, v36, v128
	v_fmac_f32_e32 v45, v34, v130
	v_fmac_f32_e32 v45, v35, v131
	v_add_f32_e32 v51, v60, v45
	ds_read_b128 v[124:127], v67 offset:60416
	s_waitcnt lgkmcnt(6)
; #define LAS __attribute__((address_space(3)))
; __device__ __forceinline__ unsigned cvt_pk_bf16(float lo, float hi) { unsigned r; asm volatile("v_cvt_pk_bf16_f32 %0, %1, %2" : "=v"(r) : "v"(lo), "v"(hi)); return r; }
; __device__ void phase_norm_alow(const Params& P, int l, int half, LAS unsigned char* lds) {
;     ...
;         for (int i = 0; i < 4; ++i) { f32x4 h = v[i] * r * gv[i];
;             u32x2 w; w.x = cvt_pk_bf16(h[0], h[1]); w.y = cvt_pk_bf16(h[2], h[3]);
;             *(u32x2*)(H + (size_t)row * DM + i * 256 + lane * 4) = w;
; #pragma unroll
;             for (int c = 0; c < 16; ++c) { const f32x4 wv = *(const LAS f32x4*)(WaT + c * 1024 + i * 256 + lane * 4); a[c] += h[0] * wv[0] + h[1] * wv[1] + h[2] * wv[2] + h[3] * wv[3]; } }
;         float b8[8], b4[4], b2[2], b1;
;         { const bool up = (lane & 32) != 0;
; #pragma unroll
;           for (int c = 0; c < 8; ++c) { const float keep = up ? a[c + 8] : a[c], send = up ? a[c] : a[c + 8]; b8[c] = keep + __shfl_xor(send, 32); } }
;         { const bool up = (lane & 16) != 0;
; #pragma unroll
;           for (int c = 0; c < 4; ++c) { const float keep = up ? b8[c + 4] : b8[c], send = up ? b8[c] : b8[c + 4]; b4[c] = keep + __shfl_xor(send, 16); } }
;         { const bool up = (lane & 8) != 0;
; #pragma unroll
;           for (int c = 0; c < 2; ++c) { const float keep = up ? b4[c + 2] : b4[c], send = up ? b4[c] : b4[c + 2]; b2[c] = keep + __shfl_xor(send, 8); } }
;         { const bool up = (lane & 4) != 0; const float keep = up ? b2[1] : b2[0], send = up ? b2[0] : b2[1]; b1 = keep + __shfl_xor(send, 4); }
;         b1 += __shfl_xor(b1, 2); b1 += __shfl_xor(b1, 1);
;         if ((lane & 3) == 0) { const int co = ((lane >> 5) & 1) * 8 + ((lane >> 4) & 1) * 4 + ((lane >> 3) & 1) * 2 + ((lane >> 2) & 1); AL[(size_t)row * 16 + co] = b1; }
	v_mul_f32_e32 v45, v37, v101
	v_fmac_f32_e32 v45, v36, v100
	v_fmac_f32_e32 v45, v34, v102
	v_fmac_f32_e32 v45, v35, v103
	v_add_f32_e32 v58, v61, v45
	ds_read_b128 v[128:131], v67 offset:64512
	s_waitcnt lgkmcnt(6)
	v_mul_f32_e32 v45, v37, v105
	v_fmac_f32_e32 v45, v36, v104
	v_fmac_f32_e32 v45, v34, v106
	v_fmac_f32_e32 v45, v35, v107
	v_add_f32_e32 v60, v68, v45
	s_waitcnt lgkmcnt(5)
	v_mul_f32_e32 v45, v37, v109
	v_fmac_f32_e32 v45, v36, v108
	v_fmac_f32_e32 v45, v34, v110
	v_fmac_f32_e32 v45, v35, v111
	v_add_f32_e32 v61, v69, v45
	s_waitcnt lgkmcnt(4)
	v_mul_f32_e32 v45, v37, v113
	v_fmac_f32_e32 v45, v36, v112
	v_fmac_f32_e32 v45, v34, v114
	v_fmac_f32_e32 v45, v35, v115
	v_add_f32_e32 v68, v70, v45
	s_waitcnt lgkmcnt(3)
	v_mul_f32_e32 v45, v37, v117
	v_fmac_f32_e32 v45, v36, v116
	v_fmac_f32_e32 v45, v34, v118
	v_fmac_f32_e32 v45, v35, v119
	v_add_f32_e32 v69, v71, v45
	s_waitcnt lgkmcnt(2)
	v_mul_f32_e32 v45, v37, v121
	v_fmac_f32_e32 v45, v36, v120
	v_fmac_f32_e32 v45, v34, v122
	v_fmac_f32_e32 v45, v35, v123
	v_add_f32_e32 v70, v72, v45
	s_waitcnt lgkmcnt(1)
	v_mul_f32_e32 v45, v37, v125
	v_fmac_f32_e32 v45, v36, v124
	v_fmac_f32_e32 v45, v34, v126
	v_fmac_f32_e32 v45, v35, v127
	v_add_f32_e32 v71, v73, v45
	s_waitcnt lgkmcnt(0)
	v_mul_f32_e32 v37, v37, v129
	v_fmac_f32_e32 v37, v36, v128
	v_fmac_f32_e32 v37, v34, v130
	v_fmac_f32_e32 v37, v35, v131
	v_cndmask_b32_e32 v36, v39, v58, vcc
	v_add_f32_e32 v34, v38, v37
	ds_bpermute_b32 v36, v59, v36
	v_cndmask_b32_e32 v37, v40, v60, vcc
	ds_bpermute_b32 v37, v59, v37
	v_cndmask_b32_e32 v38, v41, v61, vcc
	ds_bpermute_b32 v38, v59, v38
	v_cndmask_b32_e32 v35, v58, v39, vcc
	v_cndmask_b32_e32 v39, v42, v68, vcc
	s_waitcnt lgkmcnt(2)
	v_add_f32_e32 v35, v35, v36
	v_cndmask_b32_e32 v36, v60, v40, vcc
	ds_bpermute_b32 v39, v59, v39
	v_cndmask_b32_e32 v40, v43, v69, vcc
	s_waitcnt lgkmcnt(2)
	v_add_f32_e32 v36, v36, v37
	v_cndmask_b32_e32 v37, v61, v41, vcc
	ds_bpermute_b32 v40, v59, v40
	v_cndmask_b32_e32 v41, v48, v70, vcc
	s_waitcnt lgkmcnt(2)
	v_add_f32_e32 v37, v37, v38
	v_cndmask_b32_e32 v38, v68, v42, vcc
	ds_bpermute_b32 v41, v59, v41
	v_cndmask_b32_e32 v42, v49, v71, vcc
	ds_bpermute_b32 v42, v59, v42
	s_waitcnt lgkmcnt(3)
	v_add_f32_e32 v38, v38, v39
	v_cndmask_b32_e32 v39, v69, v43, vcc
	s_waitcnt lgkmcnt(2)
	v_add_f32_e32 v39, v39, v40
	v_cndmask_b32_e32 v40, v70, v48, vcc
	s_waitcnt lgkmcnt(1)
	v_add_f32_e32 v40, v40, v41
	v_cndmask_b32_e32 v41, v71, v49, vcc
	s_waitcnt lgkmcnt(0)
	v_add_f32_e32 v41, v41, v42
	v_cndmask_b32_e32 v42, v34, v51, vcc
	v_cndmask_b32_e32 v34, v51, v34, vcc
	ds_bpermute_b32 v34, v59, v34
	s_waitcnt lgkmcnt(0)
	v_add_f32_e32 v34, v42, v34
	v_cndmask_b32_e64 v42, v39, v35, s[36:37]
	v_cndmask_b32_e64 v35, v35, v39, s[36:37]
	v_cndmask_b32_e64 v39, v40, v36, s[36:37]
	v_cndmask_b32_e64 v36, v36, v40, s[36:37]
	ds_bpermute_b32 v36, v62, v36
	ds_bpermute_b32 v35, v62, v35
	s_waitcnt lgkmcnt(1)
	v_add_f32_e32 v36, v39, v36
	v_cndmask_b32_e64 v39, v41, v37, s[36:37]
	v_cndmask_b32_e64 v37, v37, v41, s[36:37]
	ds_bpermute_b32 v37, v62, v37
	s_waitcnt lgkmcnt(1)
	v_add_f32_e32 v35, v42, v35
	s_waitcnt lgkmcnt(0)
	v_add_f32_e32 v37, v39, v37
	v_cndmask_b32_e64 v39, v34, v38, s[36:37]
	v_cndmask_b32_e64 v34, v38, v34, s[36:37]
	ds_bpermute_b32 v34, v62, v34
	v_cndmask_b32_e64 v38, v37, v35, s[38:39]
	v_cndmask_b32_e64 v35, v35, v37, s[38:39]
	ds_bpermute_b32 v35, v63, v35
	s_waitcnt lgkmcnt(1)
	v_add_f32_e32 v34, v39, v34
	v_cndmask_b32_e64 v37, v34, v36, s[38:39]
	v_cndmask_b32_e64 v34, v36, v34, s[38:39]
	ds_bpermute_b32 v34, v63, v34
	s_waitcnt lgkmcnt(1)
	v_add_f32_e32 v35, v38, v35
	s_waitcnt lgkmcnt(0)
	v_add_f32_e32 v34, v37, v34
	v_cndmask_b32_e64 v36, v34, v35, s[40:41]
	v_cndmask_b32_e64 v34, v35, v34, s[40:41]
	ds_bpermute_b32 v34, v64, v34
	s_waitcnt lgkmcnt(0)
	v_add_f32_e32 v34, v36, v34
	ds_bpermute_b32 v35, v65, v34
	s_waitcnt lgkmcnt(0)
	v_add_f32_e32 v34, v34, v35
	ds_bpermute_b32 v35, v66, v34
	s_and_saveexec_b64 s[0:1], s[42:43]
	s_cbranch_execz .LBB0_239
	v_lshl_add_u64 v[36:37], s[74:75], 0, v[52:53]
	s_waitcnt lgkmcnt(0)
	v_add_f32_e32 v34, v34, v35
	global_store_dword v[36:37], v34, off
	s_branch .LBB0_239

; #define LAS __attribute__((address_space(3)))
; __device__ __forceinline__ unsigned cvt_pk_bf16(float lo, float hi) { unsigned r; asm volatile("v_cvt_pk_bf16_f32 %0, %1, %2" : "=v"(r) : "v"(lo), "v"(hi)); return r; }
; __device__ void phase_norm_alow(const Params& P, int l, int half, LAS unsigned char* lds) {
;     ...
;         for (int i = 0; i < 4; ++i) { v[i] = nv[i]; ss += v[i][0] * v[i][0] + v[i][1] * v[i][1] + v[i][2] * v[i][2] + v[i][3] * v[i][3]; }
;         if (row + rstride < TH) {
; #pragma unroll
;             for (int i = 0; i < 4; ++i) nv[i] = *(const f32x4*)(xs + (size_t)(row + rstride) * DM + i * 256 + lane * 4);
;         }
;         ss = wave_sum(ss);
;         const float r = rsqrtf(ss * (1.0f / DM) + EPS);
;         float a[16];
; #pragma unroll
;         for (int c = 0; c < 16; ++c) a[c] = 0.f;
; #pragma unroll
;         for (int i = 0; i < 4; ++i) { f32x4 h = v[i] * r * gv[i];
;             u32x2 w; w.x = cvt_pk_bf16(h[0], h[1]); w.y = cvt_pk_bf16(h[2], h[3]);
;             *(u32x2*)(H + (size_t)row * DM + i * 256 + lane * 4) = w;
; #pragma unroll
;             for (int c = 0; c < 16; ++c) { const f32x4 wv = *(const LAS f32x4*)(WaT + c * 1024 + i * 256 + lane * 4); a[c] += h[0] * wv[0] + h[1] * wv[1] + h[2] * wv[2] + h[3] * wv[3]; } }
.LBB0_680:
	s_or_b64 exec, exec, s[30:31]
	v_mul_f32_e32 v51, v47, v47
	v_mul_f32_e32 v58, v43, v43
	v_fmac_f32_e32 v51, v46, v46
	v_fmac_f32_e32 v58, v42, v42
	v_fmac_f32_e32 v51, v48, v48
	v_fmac_f32_e32 v58, v44, v44
	v_fmac_f32_e32 v51, v49, v49
	v_fmac_f32_e32 v58, v45, v45
	v_add_f32_e32 v51, v51, v58
	v_mul_f32_e32 v58, v39, v39
	v_fmac_f32_e32 v58, v38, v38
	v_fmac_f32_e32 v58, v40, v40
	v_fmac_f32_e32 v58, v41, v41
	v_add_f32_e32 v51, v51, v58
	v_mul_f32_e32 v58, v35, v35
	v_fmac_f32_e32 v58, v34, v34
	v_fmac_f32_e32 v58, v36, v36
	v_fmac_f32_e32 v58, v37, v37
	v_add_f32_e32 v51, v51, v58
	ds_bpermute_b32 v58, v59, v51
	v_lshl_add_u64 v[68:69], s[74:75], 0, v[56:57]
	s_waitcnt lgkmcnt(0)
	v_add_f32_e32 v51, v51, v58
	ds_bpermute_b32 v58, v62, v51
	s_waitcnt lgkmcnt(0)
	v_add_f32_e32 v51, v51, v58
	ds_bpermute_b32 v58, v63, v51
	s_waitcnt lgkmcnt(0)
	v_add_f32_e32 v51, v51, v58
	ds_bpermute_b32 v58, v64, v51
	s_waitcnt lgkmcnt(0)
	v_add_f32_e32 v51, v51, v58
	ds_bpermute_b32 v58, v65, v51
	s_waitcnt lgkmcnt(0)
	v_add_f32_e32 v51, v51, v58
	ds_bpermute_b32 v58, v66, v51
	s_waitcnt lgkmcnt(0)
	v_add_f32_e32 v51, v51, v58
	v_fmamk_f32 v51, v51, 0x3a800000, v1
	v_cmp_gt_f32_e64 s[0:1], s33, v51
	v_mul_f32_e32 v58, 0x4b800000, v51
	s_nop 0
	v_cndmask_b32_e64 v51, v51, v58, s[0:1]
	v_rsq_f32_e32 v51, v51
	s_nop 0
	v_mul_f32_e32 v58, 0x45800000, v51
	v_cndmask_b32_e64 v58, v51, v58, s[0:1]
	v_pk_mul_f32 v[46:47], v[46:47], v[58:59] op_sel_hi:[1,0]
	s_mov_b32 s0, 0x3a88000
	v_pk_mul_f32 v[48:49], v[48:49], v[58:59] op_sel_hi:[1,0]
	v_pk_mul_f32 v[60:61], v[14:15], v[46:47]
	v_add_co_u32_e64 v46, s[0:1], s0, v68
	v_pk_mul_f32 v[48:49], v[16:17], v[48:49]
	v_cvt_pk_bf16_f32 v70, v60, v61
	s_nop 0
	v_addc_co_u32_e64 v47, s[0:1], 0, v69, s[0:1]
	v_cvt_pk_bf16_f32 v71, v48, v49
	global_store_dwordx2 v[46:47], v[70:71], off
	ds_read_b128 v[100:103], v67
	ds_read_b128 v[104:107], v67 offset:4096
	ds_read_b128 v[108:111], v67 offset:8192
	ds_read_b128 v[112:115], v67 offset:12288
	ds_read_b128 v[116:119], v67 offset:16384
	ds_read_b128 v[120:123], v67 offset:20480
	ds_read_b128 v[124:127], v67 offset:24576
	s_waitcnt lgkmcnt(6)
	v_mul_f32_e32 v51, v101, v61
	v_fmac_f32_e32 v51, v100, v60
	v_fmac_f32_e32 v51, v102, v48
	v_fmac_f32_e32 v51, v103, v49
	ds_read_b128 v[128:131], v67 offset:28672
	v_add_f32_e32 v69, 0, v51
	s_waitcnt lgkmcnt(6)
	v_mul_f32_e32 v51, v105, v61
	v_fmac_f32_e32 v51, v104, v60
	v_fmac_f32_e32 v51, v106, v48
	v_fmac_f32_e32 v51, v107, v49
	ds_read_b128 v[100:103], v67 offset:32768
	v_add_f32_e32 v51, 0, v51
	s_waitcnt lgkmcnt(6)
	v_mul_f32_e32 v68, v109, v61
	v_fmac_f32_e32 v68, v108, v60
	v_fmac_f32_e32 v68, v110, v48
	v_fmac_f32_e32 v68, v111, v49
	ds_read_b128 v[104:107], v67 offset:36864
	v_add_f32_e32 v68, 0, v68
	s_waitcnt lgkmcnt(6)
	v_mul_f32_e32 v71, v113, v61
	v_fmac_f32_e32 v71, v112, v60
	v_fmac_f32_e32 v71, v114, v48
	v_fmac_f32_e32 v71, v115, v49
	ds_read_b128 v[108:111], v67 offset:40960
	v_add_f32_e32 v70, 0, v71
	s_waitcnt lgkmcnt(6)
	v_mul_f32_e32 v71, v117, v61
	v_fmac_f32_e32 v71, v116, v60
	v_fmac_f32_e32 v71, v118, v48
	v_fmac_f32_e32 v71, v119, v49
	ds_read_b128 v[112:115], v67 offset:45056
	v_add_f32_e32 v71, 0, v71
	s_waitcnt lgkmcnt(6)
	v_mul_f32_e32 v73, v121, v61
	v_fmac_f32_e32 v73, v120, v60
	v_fmac_f32_e32 v73, v122, v48
	v_fmac_f32_e32 v73, v123, v49
	ds_read_b128 v[116:119], v67 offset:49152
	v_add_f32_e32 v72, 0, v73
	s_waitcnt lgkmcnt(6)
	v_mul_f32_e32 v73, v125, v61
	v_fmac_f32_e32 v73, v124, v60
	v_fmac_f32_e32 v73, v126, v48
	v_fmac_f32_e32 v73, v127, v49
	ds_read_b128 v[120:123], v67 offset:53248
	v_add_f32_e32 v73, 0, v73
	s_waitcnt lgkmcnt(6)
	v_mul_f32_e32 v75, v129, v61
	v_fmac_f32_e32 v75, v128, v60
	v_fmac_f32_e32 v75, v130, v48
	v_fmac_f32_e32 v75, v131, v49
	ds_read_b128 v[124:127], v67 offset:57344
	v_add_f32_e32 v74, 0, v75
	s_waitcnt lgkmcnt(6)
	v_mul_f32_e32 v75, v101, v61
	v_fmac_f32_e32 v75, v100, v60
	v_fmac_f32_e32 v75, v102, v48
	v_fmac_f32_e32 v75, v103, v49
	ds_read_b128 v[128:131], v67 offset:61440
	v_add_f32_e32 v75, 0, v75
	s_waitcnt lgkmcnt(6)
	v_mul_f32_e32 v77, v61, v105
	v_fmac_f32_e32 v77, v60, v104
	v_fmac_f32_e32 v77, v48, v106
	v_fmac_f32_e32 v77, v49, v107
	ds_read_b128 v[100:103], v67 offset:1024
	v_add_f32_e32 v76, 0, v77
	s_waitcnt lgkmcnt(6)
	v_mul_f32_e32 v77, v61, v109
	v_fmac_f32_e32 v77, v60, v108
	v_fmac_f32_e32 v77, v48, v110
	v_fmac_f32_e32 v77, v49, v111
	ds_read_b128 v[104:107], v67 offset:5120
	v_add_f32_e32 v77, 0, v77
	s_waitcnt lgkmcnt(6)
	v_mul_f32_e32 v79, v61, v113
	v_fmac_f32_e32 v79, v60, v112
	v_fmac_f32_e32 v79, v48, v114
	v_fmac_f32_e32 v79, v49, v115
	ds_read_b128 v[108:111], v67 offset:9216
	v_add_f32_e32 v78, 0, v79
	s_waitcnt lgkmcnt(6)
	v_mul_f32_e32 v79, v61, v117
	v_fmac_f32_e32 v79, v60, v116
	v_fmac_f32_e32 v79, v48, v118
	v_fmac_f32_e32 v79, v49, v119
	ds_read_b128 v[112:115], v67 offset:13312
	v_add_f32_e32 v79, 0, v79
	s_waitcnt lgkmcnt(6)
	v_mul_f32_e32 v81, v61, v121
	v_fmac_f32_e32 v81, v60, v120
	v_fmac_f32_e32 v81, v48, v122
	v_fmac_f32_e32 v81, v49, v123
	ds_read_b128 v[116:119], v67 offset:17408
	v_add_f32_e32 v80, 0, v81
	s_waitcnt lgkmcnt(6)
	v_mul_f32_e32 v81, v61, v125
	v_fmac_f32_e32 v81, v60, v124
	v_fmac_f32_e32 v81, v48, v126
	v_fmac_f32_e32 v81, v49, v127
	ds_read_b128 v[120:123], v67 offset:21504
	v_add_f32_e32 v81, 0, v81
	s_waitcnt lgkmcnt(6)
; #define LAS __attribute__((address_space(3)))
; __device__ __forceinline__ unsigned cvt_pk_bf16(float lo, float hi) { unsigned r; asm volatile("v_cvt_pk_bf16_f32 %0, %1, %2" : "=v"(r) : "v"(lo), "v"(hi)); return r; }
; __device__ void phase_norm_alow(const Params& P, int l, int half, LAS unsigned char* lds) {
;     ...
;         for (int i = 0; i < 4; ++i) { f32x4 h = v[i] * r * gv[i];
;             u32x2 w; w.x = cvt_pk_bf16(h[0], h[1]); w.y = cvt_pk_bf16(h[2], h[3]);
;             *(u32x2*)(H + (size_t)row * DM + i * 256 + lane * 4) = w;
; #pragma unroll
;             for (int c = 0; c < 16; ++c) { const f32x4 wv = *(const LAS f32x4*)(WaT + c * 1024 + i * 256 + lane * 4); a[c] += h[0] * wv[0] + h[1] * wv[1] + h[2] * wv[2] + h[3] * wv[3]; } }
	v_mul_f32_e32 v61, v61, v129
	v_fmac_f32_e32 v61, v60, v128
	v_fmac_f32_e32 v61, v48, v130
	v_fmac_f32_e32 v61, v49, v131
	v_add_f32_e32 v48, 0, v61
	v_pk_mul_f32 v[60:61], v[42:43], v[58:59] op_sel_hi:[1,0]
	v_pk_mul_f32 v[42:43], v[44:45], v[58:59] op_sel_hi:[1,0]
	v_pk_mul_f32 v[44:45], v[10:11], v[60:61]
	v_pk_mul_f32 v[42:43], v[12:13], v[42:43]
	v_cvt_pk_bf16_f32 v60, v44, v45
	s_nop 0
	v_cvt_pk_bf16_f32 v61, v42, v43
	ds_read_b128 v[124:127], v67 offset:25600
	global_store_dwordx2 v[46:47], v[60:61], off offset:512
	s_waitcnt lgkmcnt(6)
	v_mul_f32_e32 v49, v45, v101
	v_fmac_f32_e32 v49, v44, v100
	v_fmac_f32_e32 v49, v42, v102
	v_fmac_f32_e32 v49, v43, v103
	ds_read_b128 v[128:131], v67 offset:29696
	v_add_f32_e32 v49, v69, v49
	s_waitcnt lgkmcnt(6)
	v_mul_f32_e32 v60, v45, v105
	v_fmac_f32_e32 v60, v44, v104
	v_fmac_f32_e32 v60, v42, v106
	v_fmac_f32_e32 v60, v43, v107
	ds_read_b128 v[100:103], v67 offset:33792
	v_add_f32_e32 v51, v51, v60
	s_waitcnt lgkmcnt(6)
	v_mul_f32_e32 v60, v45, v109
	v_fmac_f32_e32 v60, v44, v108
	v_fmac_f32_e32 v60, v42, v110
	v_fmac_f32_e32 v60, v43, v111
	ds_read_b128 v[104:107], v67 offset:37888
	v_add_f32_e32 v60, v68, v60
	s_waitcnt lgkmcnt(6)
	v_mul_f32_e32 v61, v45, v113
	v_fmac_f32_e32 v61, v44, v112
	v_fmac_f32_e32 v61, v42, v114
	v_fmac_f32_e32 v61, v43, v115
	ds_read_b128 v[108:111], v67 offset:41984
	v_add_f32_e32 v61, v70, v61
	s_waitcnt lgkmcnt(6)
	v_mul_f32_e32 v68, v45, v117
	v_fmac_f32_e32 v68, v44, v116
	v_fmac_f32_e32 v68, v42, v118
	v_fmac_f32_e32 v68, v43, v119
	ds_read_b128 v[112:115], v67 offset:46080
	v_add_f32_e32 v68, v71, v68
	s_waitcnt lgkmcnt(6)
	v_mul_f32_e32 v69, v45, v121
	v_fmac_f32_e32 v69, v44, v120
	v_fmac_f32_e32 v69, v42, v122
	v_fmac_f32_e32 v69, v43, v123
	ds_read_b128 v[116:119], v67 offset:50176
	v_add_f32_e32 v69, v72, v69
	s_waitcnt lgkmcnt(6)
	v_mul_f32_e32 v70, v45, v125
	v_fmac_f32_e32 v70, v44, v124
	v_fmac_f32_e32 v70, v42, v126
	v_fmac_f32_e32 v70, v43, v127
	ds_read_b128 v[120:123], v67 offset:54272
	v_add_f32_e32 v70, v73, v70
	s_waitcnt lgkmcnt(6)
	v_mul_f32_e32 v71, v45, v129
	v_fmac_f32_e32 v71, v44, v128
	v_fmac_f32_e32 v71, v42, v130
	v_fmac_f32_e32 v71, v43, v131
	ds_read_b128 v[124:127], v67 offset:58368
	v_add_f32_e32 v71, v74, v71
	s_waitcnt lgkmcnt(6)
	v_mul_f32_e32 v72, v45, v101
	v_fmac_f32_e32 v72, v44, v100
	v_fmac_f32_e32 v72, v42, v102
	v_fmac_f32_e32 v72, v43, v103
	ds_read_b128 v[128:131], v67 offset:62464
	v_add_f32_e32 v72, v75, v72
	s_waitcnt lgkmcnt(6)
	v_mul_f32_e32 v73, v45, v105
	v_fmac_f32_e32 v73, v44, v104
	v_fmac_f32_e32 v73, v42, v106
	v_fmac_f32_e32 v73, v43, v107
	ds_read_b128 v[100:103], v67 offset:2048
	v_add_f32_e32 v73, v76, v73
	s_waitcnt lgkmcnt(6)
	v_mul_f32_e32 v74, v45, v109
	v_fmac_f32_e32 v74, v44, v108
	v_fmac_f32_e32 v74, v42, v110
	v_fmac_f32_e32 v74, v43, v111
	ds_read_b128 v[104:107], v67 offset:6144
	v_add_f32_e32 v74, v77, v74
	s_waitcnt lgkmcnt(6)
	v_mul_f32_e32 v75, v45, v113
	v_fmac_f32_e32 v75, v44, v112
	v_fmac_f32_e32 v75, v42, v114
	v_fmac_f32_e32 v75, v43, v115
	ds_read_b128 v[108:111], v67 offset:10240
	v_add_f32_e32 v75, v78, v75
	s_waitcnt lgkmcnt(6)
	v_mul_f32_e32 v76, v45, v117
	v_fmac_f32_e32 v76, v44, v116
	v_fmac_f32_e32 v76, v42, v118
	v_fmac_f32_e32 v76, v43, v119
	ds_read_b128 v[112:115], v67 offset:14336
	v_add_f32_e32 v76, v79, v76
	s_waitcnt lgkmcnt(6)
	v_mul_f32_e32 v77, v45, v121
	v_fmac_f32_e32 v77, v44, v120
	v_fmac_f32_e32 v77, v42, v122
	v_fmac_f32_e32 v77, v43, v123
	ds_read_b128 v[116:119], v67 offset:18432
	v_add_f32_e32 v77, v80, v77
	s_waitcnt lgkmcnt(6)
	v_mul_f32_e32 v78, v45, v125
	v_fmac_f32_e32 v78, v44, v124
	v_fmac_f32_e32 v78, v42, v126
	v_fmac_f32_e32 v78, v43, v127
	v_add_f32_e32 v78, v81, v78
	ds_read_b128 v[120:123], v67 offset:22528
	s_waitcnt lgkmcnt(6)
	v_mul_f32_e32 v45, v45, v129
	v_fmac_f32_e32 v45, v44, v128
	v_fmac_f32_e32 v45, v42, v130
	v_fmac_f32_e32 v45, v43, v131
	v_pk_mul_f32 v[42:43], v[38:39], v[58:59] op_sel_hi:[1,0]
	v_pk_mul_f32 v[38:39], v[40:41], v[58:59] op_sel_hi:[1,0]
	v_pk_mul_f32 v[40:41], v[6:7], v[42:43]
	v_pk_mul_f32 v[38:39], v[8:9], v[38:39]
	v_cvt_pk_bf16_f32 v42, v40, v41
	v_add_f32_e32 v79, v48, v45
	v_cvt_pk_bf16_f32 v43, v38, v39
	global_store_dwordx2 v[46:47], v[42:43], off offset:1024
	ds_read_b128 v[124:127], v67 offset:26624
	ds_read_b128 v[128:131], v67 offset:30720
	s_waitcnt lgkmcnt(7)
	v_mul_f32_e32 v43, v41, v101
	v_fmac_f32_e32 v43, v40, v100
	v_fmac_f32_e32 v43, v38, v102
	v_fmac_f32_e32 v43, v39, v103
	v_add_f32_e32 v42, v49, v43
	s_waitcnt lgkmcnt(6)
	v_mul_f32_e32 v43, v41, v105
	v_fmac_f32_e32 v43, v40, v104
	v_fmac_f32_e32 v43, v38, v106
	v_fmac_f32_e32 v43, v39, v107
	ds_read_b128 v[100:103], v67 offset:34816
	v_add_f32_e32 v43, v51, v43
	s_waitcnt lgkmcnt(6)
	v_mul_f32_e32 v44, v41, v109
	v_fmac_f32_e32 v44, v40, v108
	v_fmac_f32_e32 v44, v38, v110
	v_fmac_f32_e32 v44, v39, v111
	ds_read_b128 v[104:107], v67 offset:38912
	v_add_f32_e32 v44, v60, v44
	s_waitcnt lgkmcnt(6)
	v_mul_f32_e32 v45, v41, v113
	v_fmac_f32_e32 v45, v40, v112
	v_fmac_f32_e32 v45, v38, v114
	v_fmac_f32_e32 v45, v39, v115
	ds_read_b128 v[108:111], v67 offset:43008
	v_add_f32_e32 v45, v61, v45
	s_waitcnt lgkmcnt(6)
	v_mul_f32_e32 v48, v41, v117
	v_fmac_f32_e32 v48, v40, v116
	v_fmac_f32_e32 v48, v38, v118
	v_fmac_f32_e32 v48, v39, v119
	ds_read_b128 v[112:115], v67 offset:47104
	v_add_f32_e32 v48, v68, v48
	s_waitcnt lgkmcnt(6)
	v_mul_f32_e32 v49, v41, v121
	v_fmac_f32_e32 v49, v40, v120
	v_fmac_f32_e32 v49, v38, v122
	v_fmac_f32_e32 v49, v39, v123
	ds_read_b128 v[116:119], v67 offset:51200
	v_add_f32_e32 v49, v69, v49
	s_waitcnt lgkmcnt(6)
; #define LAS __attribute__((address_space(3)))
; __device__ __forceinline__ unsigned cvt_pk_bf16(float lo, float hi) { unsigned r; asm volatile("v_cvt_pk_bf16_f32 %0, %1, %2" : "=v"(r) : "v"(lo), "v"(hi)); return r; }
; __device__ void phase_norm_alow(const Params& P, int l, int half, LAS unsigned char* lds) {
;     ...
;         for (int i = 0; i < 4; ++i) { f32x4 h = v[i] * r * gv[i];
;             u32x2 w; w.x = cvt_pk_bf16(h[0], h[1]); w.y = cvt_pk_bf16(h[2], h[3]);
;             *(u32x2*)(H + (size_t)row * DM + i * 256 + lane * 4) = w;
; #pragma unroll
;             for (int c = 0; c < 16; ++c) { const f32x4 wv = *(const LAS f32x4*)(WaT + c * 1024 + i * 256 + lane * 4); a[c] += h[0] * wv[0] + h[1] * wv[1] + h[2] * wv[2] + h[3] * wv[3]; } }
	v_mul_f32_e32 v51, v41, v125
	v_fmac_f32_e32 v51, v40, v124
	v_fmac_f32_e32 v51, v38, v126
	v_fmac_f32_e32 v51, v39, v127
	ds_read_b128 v[120:123], v67 offset:55296
	v_add_f32_e32 v51, v70, v51
	s_waitcnt lgkmcnt(6)
	v_mul_f32_e32 v60, v41, v129
	v_fmac_f32_e32 v60, v40, v128
	v_fmac_f32_e32 v60, v38, v130
	v_fmac_f32_e32 v60, v39, v131
	v_add_f32_e32 v60, v71, v60
	ds_read_b128 v[124:127], v67 offset:59392
	s_waitcnt lgkmcnt(6)
	v_mul_f32_e32 v61, v41, v101
	v_fmac_f32_e32 v61, v40, v100
	v_fmac_f32_e32 v61, v38, v102
	v_fmac_f32_e32 v61, v39, v103
	ds_read_b128 v[128:131], v67 offset:63488
	v_add_f32_e32 v61, v72, v61
	s_waitcnt lgkmcnt(6)
	v_mul_f32_e32 v69, v41, v105
	v_fmac_f32_e32 v69, v40, v104
	v_fmac_f32_e32 v69, v38, v106
	v_fmac_f32_e32 v69, v39, v107
	v_add_f32_e32 v68, v73, v69
	ds_read_b128 v[100:103], v67 offset:3072
	s_waitcnt lgkmcnt(6)
	v_mul_f32_e32 v69, v41, v109
	v_fmac_f32_e32 v69, v40, v108
	v_fmac_f32_e32 v69, v38, v110
	v_fmac_f32_e32 v69, v39, v111
	ds_read_b128 v[104:107], v67 offset:7168
	v_add_f32_e32 v69, v74, v69
	s_waitcnt lgkmcnt(6)
	v_mul_f32_e32 v71, v41, v113
	v_fmac_f32_e32 v71, v40, v112
	v_fmac_f32_e32 v71, v38, v114
	v_fmac_f32_e32 v71, v39, v115
	v_add_f32_e32 v70, v75, v71
	ds_read_b128 v[108:111], v67 offset:11264
	s_waitcnt lgkmcnt(6)
	v_mul_f32_e32 v71, v41, v117
	v_fmac_f32_e32 v71, v40, v116
	v_fmac_f32_e32 v71, v38, v118
	v_fmac_f32_e32 v71, v39, v119
	ds_read_b128 v[112:115], v67 offset:15360
	v_add_f32_e32 v71, v76, v71
	s_waitcnt lgkmcnt(6)
	v_mul_f32_e32 v73, v41, v121
	v_fmac_f32_e32 v73, v40, v120
	v_fmac_f32_e32 v73, v38, v122
	v_fmac_f32_e32 v73, v39, v123
	v_add_f32_e32 v72, v77, v73
	ds_read_b128 v[116:119], v67 offset:19456
	s_waitcnt lgkmcnt(6)
	v_mul_f32_e32 v73, v41, v125
	v_fmac_f32_e32 v73, v40, v124
	v_fmac_f32_e32 v73, v38, v126
	v_fmac_f32_e32 v73, v39, v127
	ds_read_b128 v[120:123], v67 offset:23552
	v_add_f32_e32 v73, v78, v73
	s_waitcnt lgkmcnt(6)
	v_mul_f32_e32 v41, v41, v129
	v_fmac_f32_e32 v41, v40, v128
	v_fmac_f32_e32 v41, v38, v130
	v_fmac_f32_e32 v41, v39, v131
	v_add_f32_e32 v38, v79, v41
	v_pk_mul_f32 v[40:41], v[34:35], v[58:59] op_sel_hi:[1,0]
	v_pk_mul_f32 v[34:35], v[36:37], v[58:59] op_sel_hi:[1,0]
	v_pk_mul_f32 v[36:37], v[2:3], v[40:41]
	v_pk_mul_f32 v[34:35], v[4:5], v[34:35]
	v_cvt_pk_bf16_f32 v40, v36, v37
	s_nop 0
	v_cvt_pk_bf16_f32 v41, v34, v35
	ds_read_b128 v[124:127], v67 offset:27648
	global_store_dwordx2 v[46:47], v[40:41], off offset:1536
	s_waitcnt lgkmcnt(6)
	v_mul_f32_e32 v39, v37, v101
	v_fmac_f32_e32 v39, v36, v100
	v_fmac_f32_e32 v39, v34, v102
	v_fmac_f32_e32 v39, v35, v103
	ds_read_b128 v[128:131], v67 offset:31744
	v_add_f32_e32 v39, v42, v39
	s_waitcnt lgkmcnt(6)
	v_mul_f32_e32 v40, v37, v105
	v_fmac_f32_e32 v40, v36, v104
	v_fmac_f32_e32 v40, v34, v106
	v_fmac_f32_e32 v40, v35, v107
	ds_read_b128 v[100:103], v67 offset:35840
	v_add_f32_e32 v40, v43, v40
	s_waitcnt lgkmcnt(6)
	v_mul_f32_e32 v41, v37, v109
	v_fmac_f32_e32 v41, v36, v108
	v_fmac_f32_e32 v41, v34, v110
	v_fmac_f32_e32 v41, v35, v111
	ds_read_b128 v[104:107], v67 offset:39936
	v_add_f32_e32 v41, v44, v41
	s_waitcnt lgkmcnt(6)
	v_mul_f32_e32 v42, v37, v113
	v_fmac_f32_e32 v42, v36, v112
	v_fmac_f32_e32 v42, v34, v114
	v_fmac_f32_e32 v42, v35, v115
	v_add_f32_e32 v42, v45, v42
	ds_read_b128 v[108:111], v67 offset:44032
	s_waitcnt lgkmcnt(6)
	v_mul_f32_e32 v43, v37, v117
	v_fmac_f32_e32 v43, v36, v116
	v_fmac_f32_e32 v43, v34, v118
	v_fmac_f32_e32 v43, v35, v119
	ds_read_b128 v[112:115], v67 offset:48128
	v_add_f32_e32 v43, v48, v43
	s_waitcnt lgkmcnt(6)
	v_mul_f32_e32 v45, v37, v121
	v_fmac_f32_e32 v45, v36, v120
	v_fmac_f32_e32 v45, v34, v122
	v_fmac_f32_e32 v45, v35, v123
	v_add_f32_e32 v48, v49, v45
	ds_read_b128 v[116:119], v67 offset:52224
	s_waitcnt lgkmcnt(6)
	v_mul_f32_e32 v45, v37, v125
	v_fmac_f32_e32 v45, v36, v124
	v_fmac_f32_e32 v45, v34, v126
	v_fmac_f32_e32 v45, v35, v127
	v_add_f32_e32 v49, v51, v45
	ds_read_b128 v[120:123], v67 offset:56320
	s_waitcnt lgkmcnt(6)
	v_mul_f32_e32 v45, v37, v129
	v_fmac_f32_e32 v45, v36, v128
	v_fmac_f32_e32 v45, v34, v130
	v_fmac_f32_e32 v45, v35, v131
	v_add_f32_e32 v51, v60, v45
	ds_read_b128 v[124:127], v67 offset:60416
	s_waitcnt lgkmcnt(6)
; #define LAS __attribute__((address_space(3)))
; __device__ void phase_norm_alow(const Params& P, int l, int half, LAS unsigned char* lds) {
;     ...
;             for (int c = 0; c < 16; ++c) { const f32x4 wv = *(const LAS f32x4*)(WaT + c * 1024 + i * 256 + lane * 4); a[c] += h[0] * wv[0] + h[1] * wv[1] + h[2] * wv[2] + h[3] * wv[3]; } }
;         float b8[8], b4[4], b2[2], b1;
;         { const bool up = (lane & 32) != 0;
; #pragma unroll
;           for (int c = 0; c < 8; ++c) { const float keep = up ? a[c + 8] : a[c], send = up ? a[c] : a[c + 8]; b8[c] = keep + __shfl_xor(send, 32); } }
;         { const bool up = (lane & 16) != 0;
; #pragma unroll
;           for (int c = 0; c < 4; ++c) { const float keep = up ? b8[c + 4] : b8[c], send = up ? b8[c] : b8[c + 4]; b4[c] = keep + __shfl_xor(send, 16); } }
;         { const bool up = (lane & 8) != 0;
; #pragma unroll
;           for (int c = 0; c < 2; ++c) { const float keep = up ? b4[c + 2] : b4[c], send = up ? b4[c] : b4[c + 2]; b2[c] = keep + __shfl_xor(send, 8); } }
;         { const bool up = (lane & 4) != 0; const float keep = up ? b2[1] : b2[0], send = up ? b2[0] : b2[1]; b1 = keep + __shfl_xor(send, 4); }
;         b1 += __shfl_xor(b1, 2); b1 += __shfl_xor(b1, 1);
;         if ((lane & 3) == 0) { const int co = ((lane >> 5) & 1) * 8 + ((lane >> 4) & 1) * 4 + ((lane >> 3) & 1) * 2 + ((lane >> 2) & 1); AL[(size_t)row * 16 + co] = b1; }
	v_mul_f32_e32 v45, v37, v101
	v_fmac_f32_e32 v45, v36, v100
	v_fmac_f32_e32 v45, v34, v102
	v_fmac_f32_e32 v45, v35, v103
	v_add_f32_e32 v58, v61, v45
	ds_read_b128 v[128:131], v67 offset:64512
	s_waitcnt lgkmcnt(6)
	v_mul_f32_e32 v45, v37, v105
	v_fmac_f32_e32 v45, v36, v104
	v_fmac_f32_e32 v45, v34, v106
	v_fmac_f32_e32 v45, v35, v107
	v_add_f32_e32 v60, v68, v45
	s_waitcnt lgkmcnt(5)
	v_mul_f32_e32 v45, v37, v109
	v_fmac_f32_e32 v45, v36, v108
	v_fmac_f32_e32 v45, v34, v110
	v_fmac_f32_e32 v45, v35, v111
	v_add_f32_e32 v61, v69, v45
	s_waitcnt lgkmcnt(4)
	v_mul_f32_e32 v45, v37, v113
	v_fmac_f32_e32 v45, v36, v112
	v_fmac_f32_e32 v45, v34, v114
	v_fmac_f32_e32 v45, v35, v115
	v_add_f32_e32 v68, v70, v45
	s_waitcnt lgkmcnt(3)
	v_mul_f32_e32 v45, v37, v117
	v_fmac_f32_e32 v45, v36, v116
	v_fmac_f32_e32 v45, v34, v118
	v_fmac_f32_e32 v45, v35, v119
	v_add_f32_e32 v69, v71, v45
	s_waitcnt lgkmcnt(2)
	v_mul_f32_e32 v45, v37, v121
	v_fmac_f32_e32 v45, v36, v120
	v_fmac_f32_e32 v45, v34, v122
	v_fmac_f32_e32 v45, v35, v123
	v_add_f32_e32 v70, v72, v45
	s_waitcnt lgkmcnt(1)
	v_mul_f32_e32 v45, v37, v125
	v_fmac_f32_e32 v45, v36, v124
	v_fmac_f32_e32 v45, v34, v126
	v_fmac_f32_e32 v45, v35, v127
	v_add_f32_e32 v71, v73, v45
	s_waitcnt lgkmcnt(0)
	v_mul_f32_e32 v37, v37, v129
	v_fmac_f32_e32 v37, v36, v128
	v_fmac_f32_e32 v37, v34, v130
	v_fmac_f32_e32 v37, v35, v131
	v_cndmask_b32_e32 v36, v39, v58, vcc
	v_add_f32_e32 v34, v38, v37
	ds_bpermute_b32 v36, v59, v36
	v_cndmask_b32_e32 v37, v40, v60, vcc
	ds_bpermute_b32 v37, v59, v37
	v_cndmask_b32_e32 v38, v41, v61, vcc
	ds_bpermute_b32 v38, v59, v38
	v_cndmask_b32_e32 v35, v58, v39, vcc
	v_cndmask_b32_e32 v39, v42, v68, vcc
	s_waitcnt lgkmcnt(2)
	v_add_f32_e32 v35, v35, v36
	v_cndmask_b32_e32 v36, v60, v40, vcc
	ds_bpermute_b32 v39, v59, v39
	v_cndmask_b32_e32 v40, v43, v69, vcc
	s_waitcnt lgkmcnt(2)
	v_add_f32_e32 v36, v36, v37
	v_cndmask_b32_e32 v37, v61, v41, vcc
	ds_bpermute_b32 v40, v59, v40
	v_cndmask_b32_e32 v41, v48, v70, vcc
	s_waitcnt lgkmcnt(2)
	v_add_f32_e32 v37, v37, v38
	v_cndmask_b32_e32 v38, v68, v42, vcc
	ds_bpermute_b32 v41, v59, v41
	v_cndmask_b32_e32 v42, v49, v71, vcc
	ds_bpermute_b32 v42, v59, v42
	s_waitcnt lgkmcnt(3)
	v_add_f32_e32 v38, v38, v39
	v_cndmask_b32_e32 v39, v69, v43, vcc
	s_waitcnt lgkmcnt(2)
	v_add_f32_e32 v39, v39, v40
	v_cndmask_b32_e32 v40, v70, v48, vcc
	s_waitcnt lgkmcnt(1)
	v_add_f32_e32 v40, v40, v41
	v_cndmask_b32_e32 v41, v71, v49, vcc
	s_waitcnt lgkmcnt(0)
	v_add_f32_e32 v41, v41, v42
	v_cndmask_b32_e32 v42, v34, v51, vcc
	v_cndmask_b32_e32 v34, v51, v34, vcc
	ds_bpermute_b32 v34, v59, v34
	s_waitcnt lgkmcnt(0)
	v_add_f32_e32 v34, v42, v34
	v_cndmask_b32_e64 v42, v39, v35, s[36:37]
	v_cndmask_b32_e64 v35, v35, v39, s[36:37]
	v_cndmask_b32_e64 v39, v40, v36, s[36:37]
	v_cndmask_b32_e64 v36, v36, v40, s[36:37]
	ds_bpermute_b32 v36, v62, v36
	ds_bpermute_b32 v35, v62, v35
	s_waitcnt lgkmcnt(1)
	v_add_f32_e32 v36, v39, v36
	v_cndmask_b32_e64 v39, v41, v37, s[36:37]
	v_cndmask_b32_e64 v37, v37, v41, s[36:37]
	ds_bpermute_b32 v37, v62, v37
	s_waitcnt lgkmcnt(1)
	v_add_f32_e32 v35, v42, v35
	s_waitcnt lgkmcnt(0)
	v_add_f32_e32 v37, v39, v37
	v_cndmask_b32_e64 v39, v34, v38, s[36:37]
	v_cndmask_b32_e64 v34, v38, v34, s[36:37]
	ds_bpermute_b32 v34, v62, v34
	v_cndmask_b32_e64 v38, v37, v35, s[38:39]
	v_cndmask_b32_e64 v35, v35, v37, s[38:39]
	ds_bpermute_b32 v35, v63, v35
	s_waitcnt lgkmcnt(1)
	v_add_f32_e32 v34, v39, v34
	v_cndmask_b32_e64 v37, v34, v36, s[38:39]
	v_cndmask_b32_e64 v34, v36, v34, s[38:39]
	ds_bpermute_b32 v34, v63, v34
	s_waitcnt lgkmcnt(1)
	v_add_f32_e32 v35, v38, v35
	s_waitcnt lgkmcnt(0)
	v_add_f32_e32 v34, v37, v34
	v_cndmask_b32_e64 v36, v34, v35, s[40:41]
	v_cndmask_b32_e64 v34, v35, v34, s[40:41]
	ds_bpermute_b32 v34, v64, v34
	s_waitcnt lgkmcnt(0)
	v_add_f32_e32 v34, v36, v34
	ds_bpermute_b32 v35, v65, v34
	s_waitcnt lgkmcnt(0)
	v_add_f32_e32 v34, v34, v35
	ds_bpermute_b32 v35, v66, v34
	s_and_saveexec_b64 s[0:1], s[42:43]
	s_cbranch_execz .LBB0_677
	v_lshl_add_u64 v[36:37], s[74:75], 0, v[54:55]
	s_waitcnt lgkmcnt(0)
	v_add_f32_e32 v34, v34, v35
	global_store_dword v[36:37], v34, off
	s_branch .LBB0_677

; #define LAS __attribute__((address_space(3)))
; __device__ __forceinline__ unsigned cvt_pk_bf16(float lo, float hi) { unsigned r; asm volatile("v_cvt_pk_bf16_f32 %0, %1, %2" : "=v"(r) : "v"(lo), "v"(hi)); return r; }
; __device__ void phase_norm_alow(const Params& P, int l, int half, LAS unsigned char* lds) {
;     ...
;         f32x4 v[4]; float ss = 0.f;
; #pragma unroll
;         for (int i = 0; i < 4; ++i) { v[i] = nv[i]; ss += v[i][0] * v[i][0] + v[i][1] * v[i][1] + v[i][2] * v[i][2] + v[i][3] * v[i][3]; }
;         if (row + rstride < TH) {
; #pragma unroll
;             for (int i = 0; i < 4; ++i) nv[i] = *(const f32x4*)(xs + (size_t)(row + rstride) * DM + i * 256 + lane * 4);
;         }
;         ss = wave_sum(ss);
;         const float r = rsqrtf(ss * (1.0f / DM) + EPS);
;         float a[16];
; #pragma unroll
;         for (int c = 0; c < 16; ++c) a[c] = 0.f;
; #pragma unroll
;         for (int i = 0; i < 4; ++i) { f32x4 h = v[i] * r * gv[i];
;             u32x2 w; w.x = cvt_pk_bf16(h[0], h[1]); w.y = cvt_pk_bf16(h[2], h[3]);
;             *(u32x2*)(H + (size_t)row * DM + i * 256 + lane * 4) = w;
; #pragma unroll
;             for (int c = 0; c < 16; ++c) { const f32x4 wv = *(const LAS f32x4*)(WaT + c * 1024 + i * 256 + lane * 4); a[c] += h[0] * wv[0] + h[1] * wv[1] + h[2] * wv[2] + h[3] * wv[3]; } }
.LBB0_755:
	s_or_b64 exec, exec, s[46:47]
	v_mul_f32_e32 v51, v47, v47
	v_mul_f32_e32 v58, v43, v43
	v_fmac_f32_e32 v51, v46, v46
	v_fmac_f32_e32 v58, v42, v42
	v_fmac_f32_e32 v51, v48, v48
	v_fmac_f32_e32 v58, v44, v44
	v_fmac_f32_e32 v51, v49, v49
	v_fmac_f32_e32 v58, v45, v45
	v_add_f32_e32 v51, v51, v58
	v_mul_f32_e32 v58, v39, v39
	v_fmac_f32_e32 v58, v38, v38
	v_fmac_f32_e32 v58, v40, v40
	v_fmac_f32_e32 v58, v41, v41
	v_add_f32_e32 v51, v51, v58
	v_mul_f32_e32 v58, v35, v35
	v_fmac_f32_e32 v58, v34, v34
	v_fmac_f32_e32 v58, v36, v36
	v_fmac_f32_e32 v58, v37, v37
	v_add_f32_e32 v51, v51, v58
	ds_bpermute_b32 v58, v62, v51
	s_mov_b32 s2, 0x3a88000
	s_waitcnt lgkmcnt(0)
	v_add_f32_e32 v51, v51, v58
	ds_bpermute_b32 v58, v63, v51
	s_waitcnt lgkmcnt(0)
	v_add_f32_e32 v51, v51, v58
	ds_bpermute_b32 v58, v64, v51
	s_waitcnt lgkmcnt(0)
	v_add_f32_e32 v51, v51, v58
	ds_bpermute_b32 v58, v65, v51
	s_waitcnt lgkmcnt(0)
	v_add_f32_e32 v51, v51, v58
	ds_bpermute_b32 v58, v66, v51
	s_waitcnt lgkmcnt(0)
	v_add_f32_e32 v51, v51, v58
	ds_bpermute_b32 v60, v67, v51
	v_lshl_add_u64 v[58:59], s[74:75], 0, v[52:53]
	v_add_co_u32_e64 v58, s[46:47], s2, v58
	s_waitcnt lgkmcnt(0)
	v_add_f32_e32 v51, v51, v60
	v_fmamk_f32 v51, v51, 0x3a800000, v1
	v_mul_f32_e32 v60, 0x4b800000, v51
	v_cmp_gt_f32_e64 s[0:1], s33, v51
	v_addc_co_u32_e64 v59, s[46:47], 0, v59, s[46:47]
	s_nop 0
	v_cndmask_b32_e64 v51, v51, v60, s[0:1]
	v_rsq_f32_e32 v51, v51
	s_nop 0
	v_mul_f32_e32 v60, 0x45800000, v51
	v_cndmask_b32_e64 v60, v51, v60, s[0:1]
	v_pk_mul_f32 v[46:47], v[46:47], v[60:61] op_sel_hi:[1,0]
	v_pk_mul_f32 v[48:49], v[48:49], v[60:61] op_sel_hi:[1,0]
	s_waitcnt vmcnt(0)
	v_pk_mul_f32 v[82:83], v[14:15], v[46:47]
	v_pk_mul_f32 v[80:81], v[16:17], v[48:49]
	v_cvt_pk_bf16_f32 v84, v82, v83
	v_pk_mul_f32 v[42:43], v[42:43], v[60:61] op_sel_hi:[1,0]
	v_cvt_pk_bf16_f32 v85, v80, v81
	ds_read_b128 v[100:103], v61
	ds_read_b128 v[104:107], v61 offset:4096
	ds_read_b128 v[108:111], v61 offset:8192
	ds_read_b128 v[112:115], v61 offset:12288
	ds_read_b128 v[116:119], v61 offset:16384
	ds_read_b128 v[120:123], v61 offset:20480
	ds_read_b128 v[124:127], v61 offset:24576
	ds_read_b128 v[128:131], v61 offset:28672
	ds_read_b128 v[132:135], v61 offset:32768
	ds_read_b128 v[136:139], v61 offset:36864
	global_store_dwordx2 v[58:59], v[84:85], off
	s_waitcnt lgkmcnt(9)
	v_mul_f32_e32 v47, v101, v83
	v_fmac_f32_e32 v47, v100, v82
	s_waitcnt lgkmcnt(7)
	v_mul_f32_e32 v46, v109, v83
	v_fmac_f32_e32 v46, v108, v82
	v_mul_f32_e32 v51, v105, v83
	v_fmac_f32_e32 v47, v102, v80
	v_fmac_f32_e32 v46, v110, v80
	v_fmac_f32_e32 v51, v104, v82
	v_fmac_f32_e32 v47, v103, v81
	v_fmac_f32_e32 v46, v111, v81
	s_waitcnt lgkmcnt(6)
	v_mul_f32_e32 v68, v113, v83
	v_add_f32_e32 v84, 0, v47
	v_add_f32_e32 v74, 0, v46
	v_fmac_f32_e32 v68, v112, v82
	ds_read_b128 v[100:103], v61 offset:40960
	v_fmac_f32_e32 v68, v114, v80
	v_fmac_f32_e32 v51, v106, v80
	v_fmac_f32_e32 v68, v115, v81
	v_fmac_f32_e32 v51, v107, v81
	v_add_f32_e32 v75, 0, v68
	ds_read_b128 v[104:107], v61 offset:45056
	s_waitcnt lgkmcnt(7)
	v_mul_f32_e32 v47, v117, v83
	v_fmac_f32_e32 v47, v116, v82
	v_fmac_f32_e32 v47, v118, v80
	v_fmac_f32_e32 v47, v119, v81
	s_waitcnt lgkmcnt(6)
	v_mul_f32_e32 v69, v121, v83
	v_add_f32_e32 v76, 0, v47
	v_fmac_f32_e32 v69, v120, v82
	ds_read_b128 v[108:111], v61 offset:49152
	v_fmac_f32_e32 v69, v122, v80
	v_fmac_f32_e32 v69, v123, v81
	v_add_f32_e32 v77, 0, v69
	ds_read_b128 v[112:115], v61 offset:53248
	s_waitcnt lgkmcnt(7)
	v_mul_f32_e32 v47, v125, v83
	v_fmac_f32_e32 v47, v124, v82
	v_fmac_f32_e32 v47, v126, v80
	v_fmac_f32_e32 v47, v127, v81
	s_waitcnt lgkmcnt(6)
	v_mul_f32_e32 v69, v129, v83
	v_add_f32_e32 v78, 0, v47
	v_fmac_f32_e32 v69, v128, v82
	ds_read_b128 v[116:119], v61 offset:57344
	v_fmac_f32_e32 v69, v130, v80
	v_fmac_f32_e32 v69, v131, v81
	v_add_f32_e32 v79, 0, v69
	ds_read_b128 v[120:123], v61 offset:61440
	s_waitcnt lgkmcnt(7)
	v_mul_f32_e32 v47, v133, v83
	v_fmac_f32_e32 v47, v132, v82
	v_fmac_f32_e32 v47, v134, v80
	v_fmac_f32_e32 v47, v135, v81
	s_waitcnt lgkmcnt(6)
	v_mul_f32_e32 v69, v83, v137
	v_add_f32_e32 v85, 0, v47
	v_fmac_f32_e32 v69, v82, v136
	ds_read_b128 v[124:127], v61 offset:1024
	v_fmac_f32_e32 v69, v80, v138
	v_fmac_f32_e32 v69, v81, v139
	v_add_f32_e32 v86, 0, v69
	ds_read_b128 v[128:131], v61 offset:5120
	s_waitcnt lgkmcnt(7)
	v_mul_f32_e32 v47, v83, v101
	v_fmac_f32_e32 v47, v82, v100
	v_fmac_f32_e32 v47, v80, v102
	v_fmac_f32_e32 v47, v81, v103
	s_waitcnt lgkmcnt(6)
	v_mul_f32_e32 v69, v83, v105
	v_add_f32_e32 v87, 0, v47
	v_fmac_f32_e32 v69, v82, v104
	ds_read_b128 v[132:135], v61 offset:9216
	v_fmac_f32_e32 v69, v80, v106
	v_fmac_f32_e32 v69, v81, v107
	v_add_f32_e32 v88, 0, v69
	ds_read_b128 v[136:139], v61 offset:13312
	s_waitcnt lgkmcnt(7)
	v_mul_f32_e32 v47, v83, v109
	v_fmac_f32_e32 v47, v82, v108
	v_fmac_f32_e32 v47, v80, v110
	v_fmac_f32_e32 v47, v81, v111
	s_waitcnt lgkmcnt(6)
	v_mul_f32_e32 v69, v83, v113
	v_add_f32_e32 v89, 0, v47
	v_fmac_f32_e32 v69, v82, v112
	ds_read_b128 v[100:103], v61 offset:17408
	v_fmac_f32_e32 v69, v80, v114
	v_fmac_f32_e32 v69, v81, v115
	v_add_f32_e32 v90, 0, v69
	ds_read_b128 v[104:107], v61 offset:21504
	s_waitcnt lgkmcnt(7)
	v_mul_f32_e32 v47, v83, v117
	v_fmac_f32_e32 v47, v82, v116
	v_fmac_f32_e32 v47, v80, v118
	v_fmac_f32_e32 v47, v81, v119
	s_waitcnt lgkmcnt(6)
; #define LAS __attribute__((address_space(3)))
; __device__ __forceinline__ unsigned cvt_pk_bf16(float lo, float hi) { unsigned r; asm volatile("v_cvt_pk_bf16_f32 %0, %1, %2" : "=v"(r) : "v"(lo), "v"(hi)); return r; }
; __device__ void phase_norm_alow(const Params& P, int l, int half, LAS unsigned char* lds) {
;     ...
;         for (int i = 0; i < 4; ++i) { f32x4 h = v[i] * r * gv[i];
;             u32x2 w; w.x = cvt_pk_bf16(h[0], h[1]); w.y = cvt_pk_bf16(h[2], h[3]);
;             *(u32x2*)(H + (size_t)row * DM + i * 256 + lane * 4) = w;
; #pragma unroll
;             for (int c = 0; c < 16; ++c) { const f32x4 wv = *(const LAS f32x4*)(WaT + c * 1024 + i * 256 + lane * 4); a[c] += h[0] * wv[0] + h[1] * wv[1] + h[2] * wv[2] + h[3] * wv[3]; } }
	v_mul_f32_e32 v48, v83, v121
	v_pk_mul_f32 v[44:45], v[44:45], v[60:61] op_sel_hi:[1,0]
	v_add_f32_e32 v91, 0, v47
	v_fmac_f32_e32 v48, v82, v120
	v_pk_mul_f32 v[68:69], v[12:13], v[44:45]
	v_pk_mul_f32 v[72:73], v[10:11], v[42:43]
	v_fmac_f32_e32 v48, v80, v122
	v_cvt_pk_bf16_f32 v46, v72, v73
	v_cvt_pk_bf16_f32 v47, v68, v69
	ds_read_b128 v[108:111], v61 offset:25600
	v_fmac_f32_e32 v48, v81, v123
	v_add_f32_e32 v80, 0, v48
	global_store_dwordx2 v[58:59], v[46:47], off offset:512
	ds_read_b128 v[112:115], v61 offset:29696
	s_waitcnt lgkmcnt(7)
	v_mul_f32_e32 v43, v73, v125
	v_fmac_f32_e32 v43, v72, v124
	v_fmac_f32_e32 v43, v68, v126
	v_fmac_f32_e32 v43, v69, v127
	s_waitcnt lgkmcnt(6)
	v_mul_f32_e32 v47, v73, v129
	v_add_f32_e32 v81, v84, v43
	v_fmac_f32_e32 v47, v72, v128
	ds_read_b128 v[116:119], v61 offset:33792
	v_fmac_f32_e32 v47, v68, v130
	v_add_f32_e32 v51, 0, v51
	v_fmac_f32_e32 v47, v69, v131
	v_add_f32_e32 v51, v51, v47
	ds_read_b128 v[120:123], v61 offset:37888
	s_waitcnt lgkmcnt(7)
	v_mul_f32_e32 v43, v73, v133
	v_fmac_f32_e32 v43, v72, v132
	v_fmac_f32_e32 v43, v68, v134
	v_fmac_f32_e32 v43, v69, v135
	s_waitcnt lgkmcnt(6)
	v_mul_f32_e32 v47, v73, v137
	v_add_f32_e32 v74, v74, v43
	v_fmac_f32_e32 v47, v72, v136
	ds_read_b128 v[124:127], v61 offset:41984
	v_fmac_f32_e32 v47, v68, v138
	v_fmac_f32_e32 v47, v69, v139
	v_add_f32_e32 v75, v75, v47
	ds_read_b128 v[128:131], v61 offset:46080
	s_waitcnt lgkmcnt(7)
	v_mul_f32_e32 v43, v73, v101
	v_fmac_f32_e32 v43, v72, v100
	v_fmac_f32_e32 v43, v68, v102
	v_fmac_f32_e32 v43, v69, v103
	s_waitcnt lgkmcnt(6)
	v_mul_f32_e32 v47, v73, v105
	v_add_f32_e32 v76, v76, v43
	v_fmac_f32_e32 v47, v72, v104
	ds_read_b128 v[132:135], v61 offset:50176
	v_fmac_f32_e32 v47, v68, v106
	v_fmac_f32_e32 v47, v69, v107
	v_add_f32_e32 v77, v77, v47
	ds_read_b128 v[136:139], v61 offset:54272
	s_waitcnt lgkmcnt(7)
	v_mul_f32_e32 v43, v73, v109
	v_fmac_f32_e32 v43, v72, v108
	v_fmac_f32_e32 v43, v68, v110
	v_fmac_f32_e32 v43, v69, v111
	s_waitcnt lgkmcnt(6)
	v_mul_f32_e32 v47, v73, v113
	v_add_f32_e32 v78, v78, v43
	v_fmac_f32_e32 v47, v72, v112
	ds_read_b128 v[100:103], v61 offset:58368
	v_fmac_f32_e32 v47, v68, v114
	v_fmac_f32_e32 v47, v69, v115
	v_add_f32_e32 v79, v79, v47
	ds_read_b128 v[104:107], v61 offset:62464
	s_waitcnt lgkmcnt(7)
	v_mul_f32_e32 v43, v73, v117
	v_fmac_f32_e32 v43, v72, v116
	v_fmac_f32_e32 v43, v68, v118
	v_fmac_f32_e32 v43, v69, v119
	s_waitcnt lgkmcnt(6)
	v_mul_f32_e32 v47, v73, v121
	v_add_f32_e32 v82, v85, v43
	v_fmac_f32_e32 v47, v72, v120
	ds_read_b128 v[108:111], v61 offset:2048
	v_fmac_f32_e32 v47, v68, v122
	v_fmac_f32_e32 v47, v69, v123
	v_add_f32_e32 v83, v86, v47
	ds_read_b128 v[112:115], v61 offset:6144
	s_waitcnt lgkmcnt(7)
	v_mul_f32_e32 v43, v73, v125
	v_fmac_f32_e32 v43, v72, v124
	v_fmac_f32_e32 v43, v68, v126
	v_fmac_f32_e32 v43, v69, v127
	s_waitcnt lgkmcnt(6)
	v_mul_f32_e32 v47, v73, v129
	v_add_f32_e32 v84, v87, v43
	v_fmac_f32_e32 v47, v72, v128
	ds_read_b128 v[116:119], v61 offset:10240
	v_fmac_f32_e32 v47, v68, v130
	v_fmac_f32_e32 v47, v69, v131
	v_add_f32_e32 v85, v88, v47
	ds_read_b128 v[120:123], v61 offset:14336
	s_waitcnt lgkmcnt(7)
	v_mul_f32_e32 v43, v73, v133
	v_fmac_f32_e32 v43, v72, v132
	v_fmac_f32_e32 v43, v68, v134
	v_fmac_f32_e32 v43, v69, v135
	s_waitcnt lgkmcnt(6)
	v_mul_f32_e32 v47, v73, v137
	v_add_f32_e32 v86, v89, v43
	v_fmac_f32_e32 v47, v72, v136
	ds_read_b128 v[124:127], v61 offset:18432
	v_fmac_f32_e32 v47, v68, v138
	v_fmac_f32_e32 v47, v69, v139
	v_add_f32_e32 v87, v90, v47
	ds_read_b128 v[128:131], v61 offset:22528
	s_waitcnt lgkmcnt(7)
	v_mul_f32_e32 v43, v73, v101
	v_fmac_f32_e32 v43, v72, v100
	v_fmac_f32_e32 v43, v68, v102
	v_fmac_f32_e32 v43, v69, v103
	s_waitcnt lgkmcnt(6)
	v_mul_f32_e32 v44, v73, v105
	v_pk_mul_f32 v[38:39], v[38:39], v[60:61] op_sel_hi:[1,0]
	v_pk_mul_f32 v[40:41], v[40:41], v[60:61] op_sel_hi:[1,0]
	v_add_f32_e32 v88, v91, v43
	v_fmac_f32_e32 v44, v72, v104
	v_pk_mul_f32 v[46:47], v[8:9], v[40:41]
	v_pk_mul_f32 v[70:71], v[6:7], v[38:39]
	v_fmac_f32_e32 v44, v68, v106
	v_cvt_pk_bf16_f32 v42, v70, v71
	v_cvt_pk_bf16_f32 v43, v46, v47
	ds_read_b128 v[132:135], v61 offset:26624
	v_fmac_f32_e32 v44, v69, v107
	v_add_f32_e32 v72, v80, v44
	global_store_dwordx2 v[58:59], v[42:43], off offset:1024
	ds_read_b128 v[136:139], v61 offset:30720
	s_waitcnt lgkmcnt(7)
	v_mul_f32_e32 v39, v71, v109
	v_fmac_f32_e32 v39, v70, v108
	v_fmac_f32_e32 v39, v46, v110
	v_fmac_f32_e32 v39, v47, v111
	v_add_f32_e32 v73, v81, v39
	s_waitcnt lgkmcnt(6)
	v_mul_f32_e32 v43, v71, v113
	ds_read_b128 v[100:103], v61 offset:34816
	v_fmac_f32_e32 v43, v70, v112
	v_fmac_f32_e32 v43, v46, v114
	v_fmac_f32_e32 v43, v47, v115
	v_add_f32_e32 v51, v51, v43
	ds_read_b128 v[104:107], v61 offset:38912
	s_waitcnt lgkmcnt(7)
	v_mul_f32_e32 v39, v71, v117
	v_fmac_f32_e32 v39, v70, v116
	v_fmac_f32_e32 v39, v46, v118
	v_fmac_f32_e32 v39, v47, v119
	v_add_f32_e32 v74, v74, v39
	s_waitcnt lgkmcnt(6)
	v_mul_f32_e32 v43, v71, v121
	ds_read_b128 v[108:111], v61 offset:43008
	v_fmac_f32_e32 v43, v70, v120
	v_fmac_f32_e32 v43, v46, v122
	v_fmac_f32_e32 v43, v47, v123
	v_add_f32_e32 v75, v75, v43
	ds_read_b128 v[112:115], v61 offset:47104
	s_waitcnt lgkmcnt(7)
	v_mul_f32_e32 v39, v71, v125
	v_fmac_f32_e32 v39, v70, v124
	v_fmac_f32_e32 v39, v46, v126
	v_fmac_f32_e32 v39, v47, v127
	v_add_f32_e32 v76, v76, v39
	s_waitcnt lgkmcnt(6)
	v_mul_f32_e32 v43, v71, v129
	ds_read_b128 v[116:119], v61 offset:51200
	v_fmac_f32_e32 v43, v70, v128
	v_fmac_f32_e32 v43, v46, v130
	v_fmac_f32_e32 v43, v47, v131
	v_add_f32_e32 v77, v77, v43
	ds_read_b128 v[120:123], v61 offset:55296
	s_waitcnt lgkmcnt(7)
; #define LAS __attribute__((address_space(3)))
; __device__ __forceinline__ unsigned cvt_pk_bf16(float lo, float hi) { unsigned r; asm volatile("v_cvt_pk_bf16_f32 %0, %1, %2" : "=v"(r) : "v"(lo), "v"(hi)); return r; }
; __device__ void phase_norm_alow(const Params& P, int l, int half, LAS unsigned char* lds) {
;     ...
;         for (int i = 0; i < 4; ++i) { f32x4 h = v[i] * r * gv[i];
;             u32x2 w; w.x = cvt_pk_bf16(h[0], h[1]); w.y = cvt_pk_bf16(h[2], h[3]);
;             *(u32x2*)(H + (size_t)row * DM + i * 256 + lane * 4) = w;
; #pragma unroll
;             for (int c = 0; c < 16; ++c) { const f32x4 wv = *(const LAS f32x4*)(WaT + c * 1024 + i * 256 + lane * 4); a[c] += h[0] * wv[0] + h[1] * wv[1] + h[2] * wv[2] + h[3] * wv[3]; } }
	v_mul_f32_e32 v39, v71, v133
	v_fmac_f32_e32 v39, v70, v132
	v_fmac_f32_e32 v39, v46, v134
	v_fmac_f32_e32 v39, v47, v135
	v_add_f32_e32 v78, v78, v39
	s_waitcnt lgkmcnt(6)
	v_mul_f32_e32 v43, v71, v137
	ds_read_b128 v[124:127], v61 offset:59392
	v_fmac_f32_e32 v43, v70, v136
	v_fmac_f32_e32 v43, v46, v138
	v_fmac_f32_e32 v43, v47, v139
	v_add_f32_e32 v79, v79, v43
	ds_read_b128 v[128:131], v61 offset:63488
	s_waitcnt lgkmcnt(7)
	v_mul_f32_e32 v39, v71, v101
	v_fmac_f32_e32 v39, v70, v100
	v_fmac_f32_e32 v39, v46, v102
	v_fmac_f32_e32 v39, v47, v103
	v_add_f32_e32 v80, v82, v39
	s_waitcnt lgkmcnt(6)
	v_mul_f32_e32 v43, v71, v105
	ds_read_b128 v[132:135], v61 offset:3072
	v_fmac_f32_e32 v43, v70, v104
	v_fmac_f32_e32 v43, v46, v106
	v_fmac_f32_e32 v43, v47, v107
	v_add_f32_e32 v81, v83, v43
	ds_read_b128 v[136:139], v61 offset:7168
	s_waitcnt lgkmcnt(7)
	v_mul_f32_e32 v39, v71, v109
	v_fmac_f32_e32 v39, v70, v108
	v_fmac_f32_e32 v39, v46, v110
	v_fmac_f32_e32 v39, v47, v111
	v_add_f32_e32 v82, v84, v39
	s_waitcnt lgkmcnt(6)
	v_mul_f32_e32 v43, v71, v113
	ds_read_b128 v[100:103], v61 offset:11264
	v_fmac_f32_e32 v43, v70, v112
	v_fmac_f32_e32 v43, v46, v114
	v_fmac_f32_e32 v43, v47, v115
	v_add_f32_e32 v83, v85, v43
	ds_read_b128 v[104:107], v61 offset:15360
	s_waitcnt lgkmcnt(7)
	v_mul_f32_e32 v39, v71, v117
	v_fmac_f32_e32 v39, v70, v116
	v_fmac_f32_e32 v39, v46, v118
	v_fmac_f32_e32 v39, v47, v119
	v_add_f32_e32 v84, v86, v39
	s_waitcnt lgkmcnt(6)
	v_mul_f32_e32 v43, v71, v121
	ds_read_b128 v[108:111], v61 offset:19456
	v_fmac_f32_e32 v43, v70, v120
	v_fmac_f32_e32 v43, v46, v122
	v_fmac_f32_e32 v43, v47, v123
	v_add_f32_e32 v85, v87, v43
	ds_read_b128 v[112:115], v61 offset:23552
	s_waitcnt lgkmcnt(7)
	v_mul_f32_e32 v39, v71, v125
	v_fmac_f32_e32 v39, v70, v124
	v_fmac_f32_e32 v39, v46, v126
	v_fmac_f32_e32 v39, v47, v127
	v_pk_mul_f32 v[34:35], v[34:35], v[60:61] op_sel_hi:[1,0]
	v_pk_mul_f32 v[36:37], v[36:37], v[60:61] op_sel_hi:[1,0]
	v_add_f32_e32 v86, v88, v39
	s_waitcnt lgkmcnt(6)
	v_mul_f32_e32 v40, v71, v129
	v_pk_mul_f32 v[48:49], v[4:5], v[36:37]
	v_pk_mul_f32 v[68:69], v[2:3], v[34:35]
	v_fmac_f32_e32 v40, v70, v128
	v_cvt_pk_bf16_f32 v34, v68, v69
	v_cvt_pk_bf16_f32 v35, v48, v49
	ds_read_b128 v[116:119], v61 offset:27648
	v_fmac_f32_e32 v40, v46, v130
	v_fmac_f32_e32 v40, v47, v131
	v_add_f32_e32 v44, v72, v40
	ds_read_b128 v[120:123], v61 offset:31744
	s_waitcnt lgkmcnt(7)
	v_mul_f32_e32 v37, v69, v133
	v_fmac_f32_e32 v37, v68, v132
	v_fmac_f32_e32 v37, v48, v134
	v_fmac_f32_e32 v37, v49, v135
	v_add_f32_e32 v45, v73, v37
	s_waitcnt lgkmcnt(6)
	v_mul_f32_e32 v41, v69, v137
	ds_read_b128 v[124:127], v61 offset:35840
	v_fmac_f32_e32 v41, v68, v136
	v_fmac_f32_e32 v41, v48, v138
	v_fmac_f32_e32 v41, v49, v139
	v_add_f32_e32 v46, v51, v41
	ds_read_b128 v[128:131], v61 offset:39936
	s_waitcnt lgkmcnt(7)
	v_mul_f32_e32 v37, v69, v101
	v_fmac_f32_e32 v37, v68, v100
	v_fmac_f32_e32 v37, v48, v102
	v_fmac_f32_e32 v37, v49, v103
	v_add_f32_e32 v47, v74, v37
	s_waitcnt lgkmcnt(6)
	v_mul_f32_e32 v41, v69, v105
	ds_read_b128 v[132:135], v61 offset:44032
	v_fmac_f32_e32 v41, v68, v104
	v_fmac_f32_e32 v41, v48, v106
	v_fmac_f32_e32 v41, v49, v107
	v_add_f32_e32 v51, v75, v41
	ds_read_b128 v[136:139], v61 offset:48128
	s_waitcnt lgkmcnt(7)
	v_mul_f32_e32 v37, v69, v109
	v_fmac_f32_e32 v37, v68, v108
	v_fmac_f32_e32 v37, v48, v110
	v_fmac_f32_e32 v37, v49, v111
	v_add_f32_e32 v60, v76, v37
	s_waitcnt lgkmcnt(6)
	v_mul_f32_e32 v41, v69, v113
	ds_read_b128 v[100:103], v61 offset:52224
	v_fmac_f32_e32 v41, v68, v112
	v_fmac_f32_e32 v41, v48, v114
	v_fmac_f32_e32 v41, v49, v115
	v_add_f32_e32 v70, v77, v41
	ds_read_b128 v[104:107], v61 offset:56320
	s_waitcnt lgkmcnt(7)
	v_mul_f32_e32 v37, v69, v117
	v_fmac_f32_e32 v37, v68, v116
	v_fmac_f32_e32 v37, v48, v118
	v_fmac_f32_e32 v37, v49, v119
	v_add_f32_e32 v71, v78, v37
	s_waitcnt lgkmcnt(6)
	v_mul_f32_e32 v41, v69, v121
	ds_read_b128 v[108:111], v61 offset:60416
	v_fmac_f32_e32 v41, v68, v120
	v_fmac_f32_e32 v41, v48, v122
	v_fmac_f32_e32 v41, v49, v123
	v_add_f32_e32 v72, v79, v41
	ds_read_b128 v[112:115], v61 offset:64512
	s_waitcnt lgkmcnt(7)
; #define LAS __attribute__((address_space(3)))
; __device__ void phase_norm_alow(const Params& P, int l, int half, LAS unsigned char* lds) {
;     ...
;             for (int c = 0; c < 16; ++c) { const f32x4 wv = *(const LAS f32x4*)(WaT + c * 1024 + i * 256 + lane * 4); a[c] += h[0] * wv[0] + h[1] * wv[1] + h[2] * wv[2] + h[3] * wv[3]; } }
;         float b8[8], b4[4], b2[2], b1;
;         { const bool up = (lane & 32) != 0;
; #pragma unroll
;           for (int c = 0; c < 8; ++c) { const float keep = up ? a[c + 8] : a[c], send = up ? a[c] : a[c + 8]; b8[c] = keep + __shfl_xor(send, 32); } }
;         { const bool up = (lane & 16) != 0;
; #pragma unroll
;           for (int c = 0; c < 4; ++c) { const float keep = up ? b8[c + 4] : b8[c], send = up ? b8[c] : b8[c + 4]; b4[c] = keep + __shfl_xor(send, 16); } }
;         { const bool up = (lane & 8) != 0;
; #pragma unroll
;           for (int c = 0; c < 2; ++c) { const float keep = up ? b4[c + 2] : b4[c], send = up ? b4[c] : b4[c + 2]; b2[c] = keep + __shfl_xor(send, 8); } }
;         { const bool up = (lane & 4) != 0; const float keep = up ? b2[1] : b2[0], send = up ? b2[0] : b2[1]; b1 = keep + __shfl_xor(send, 4); }
;         b1 += __shfl_xor(b1, 2); b1 += __shfl_xor(b1, 1);
;         if ((lane & 3) == 0) { const int co = ((lane >> 5) & 1) * 8 + ((lane >> 4) & 1) * 4 + ((lane >> 3) & 1) * 2 + ((lane >> 2) & 1); AL[(size_t)row * 16 + co] = b1; }
	v_mul_f32_e32 v37, v69, v125
	v_fmac_f32_e32 v37, v68, v124
	v_fmac_f32_e32 v37, v48, v126
	v_fmac_f32_e32 v37, v49, v127
	v_add_f32_e32 v73, v80, v37
	s_waitcnt lgkmcnt(6)
	v_mul_f32_e32 v41, v69, v129
	v_fmac_f32_e32 v41, v68, v128
	v_fmac_f32_e32 v41, v48, v130
	v_fmac_f32_e32 v41, v49, v131
	v_add_f32_e32 v74, v81, v41
	s_waitcnt lgkmcnt(5)
	v_mul_f32_e32 v37, v69, v133
	v_fmac_f32_e32 v37, v68, v132
	v_fmac_f32_e32 v37, v48, v134
	v_fmac_f32_e32 v37, v49, v135
	v_add_f32_e32 v75, v82, v37
	s_waitcnt lgkmcnt(4)
	v_mul_f32_e32 v41, v69, v137
	v_fmac_f32_e32 v41, v68, v136
	v_fmac_f32_e32 v41, v48, v138
	v_fmac_f32_e32 v41, v49, v139
	v_add_f32_e32 v76, v83, v41
	s_waitcnt lgkmcnt(3)
	v_mul_f32_e32 v37, v69, v101
	v_fmac_f32_e32 v37, v68, v100
	v_fmac_f32_e32 v37, v48, v102
	v_fmac_f32_e32 v37, v49, v103
	v_add_f32_e32 v77, v84, v37
	s_waitcnt lgkmcnt(2)
	v_mul_f32_e32 v41, v69, v105
	v_fmac_f32_e32 v41, v68, v104
	v_fmac_f32_e32 v41, v48, v106
	v_fmac_f32_e32 v41, v49, v107
	v_add_f32_e32 v78, v85, v41
	s_waitcnt lgkmcnt(1)
	v_mul_f32_e32 v37, v69, v109
	v_fmac_f32_e32 v37, v68, v108
	v_fmac_f32_e32 v37, v48, v110
	v_fmac_f32_e32 v37, v49, v111
	v_add_f32_e32 v36, v86, v37
	s_waitcnt lgkmcnt(0)
	v_mul_f32_e32 v37, v69, v113
	v_cndmask_b32_e32 v39, v45, v73, vcc
	v_fmac_f32_e32 v37, v68, v112
	ds_bpermute_b32 v39, v62, v39
	v_cndmask_b32_e32 v40, v46, v74, vcc
	ds_bpermute_b32 v40, v62, v40
	v_cndmask_b32_e32 v41, v47, v75, vcc
	v_fmac_f32_e32 v37, v48, v114
	ds_bpermute_b32 v41, v62, v41
	v_cndmask_b32_e32 v42, v51, v76, vcc
	v_fmac_f32_e32 v37, v49, v115
	ds_bpermute_b32 v42, v62, v42
	v_cndmask_b32_e32 v43, v60, v77, vcc
	v_add_f32_e32 v37, v44, v37
	v_cndmask_b32_e32 v38, v73, v45, vcc
	ds_bpermute_b32 v43, v62, v43
	v_cndmask_b32_e32 v44, v70, v78, vcc
	s_waitcnt lgkmcnt(4)
	v_add_f32_e32 v38, v38, v39
	v_cndmask_b32_e32 v39, v74, v46, vcc
	ds_bpermute_b32 v44, v62, v44
	s_waitcnt lgkmcnt(4)
	v_add_f32_e32 v39, v39, v40
	v_cndmask_b32_e32 v40, v75, v47, vcc
	s_waitcnt lgkmcnt(3)
	v_add_f32_e32 v40, v40, v41
	v_cndmask_b32_e32 v41, v76, v51, vcc
	s_waitcnt lgkmcnt(2)
	v_add_f32_e32 v41, v41, v42
	v_cndmask_b32_e32 v42, v77, v60, vcc
	s_waitcnt lgkmcnt(1)
	v_add_f32_e32 v42, v42, v43
	v_cndmask_b32_e32 v43, v78, v70, vcc
	s_waitcnt lgkmcnt(0)
	v_add_f32_e32 v43, v43, v44
	v_cndmask_b32_e32 v44, v36, v71, vcc
	v_cndmask_b32_e32 v36, v71, v36, vcc
	v_cndmask_b32_e32 v45, v72, v37, vcc
	ds_bpermute_b32 v36, v62, v36
	ds_bpermute_b32 v45, v62, v45
	v_cndmask_b32_e32 v37, v37, v72, vcc
	v_cndmask_b32_e64 v46, v38, v42, s[36:37]
	v_cndmask_b32_e64 v38, v42, v38, s[36:37]
	s_waitcnt lgkmcnt(1)
	v_add_f32_e32 v36, v44, v36
	s_waitcnt lgkmcnt(0)
	v_add_f32_e32 v37, v37, v45
	v_cndmask_b32_e64 v42, v43, v39, s[36:37]
	v_cndmask_b32_e64 v39, v39, v43, s[36:37]
	v_cndmask_b32_e64 v43, v40, v36, s[36:37]
	v_cndmask_b32_e64 v44, v41, v37, s[36:37]
	ds_bpermute_b32 v46, v63, v46
	ds_bpermute_b32 v39, v63, v39
	ds_bpermute_b32 v43, v63, v43
	ds_bpermute_b32 v44, v63, v44
	v_cndmask_b32_e64 v36, v36, v40, s[36:37]
	v_cndmask_b32_e64 v37, v37, v41, s[36:37]
	s_waitcnt lgkmcnt(3)
	v_add_f32_e32 v38, v38, v46
	s_waitcnt lgkmcnt(2)
	v_add_f32_e32 v39, v42, v39
	s_waitcnt lgkmcnt(1)
	v_add_f32_e32 v36, v36, v43
	s_waitcnt lgkmcnt(0)
	v_add_f32_e32 v37, v37, v44
	v_cndmask_b32_e64 v40, v38, v36, s[38:39]
	v_cndmask_b32_e64 v41, v39, v37, s[38:39]
	ds_bpermute_b32 v40, v64, v40
	ds_bpermute_b32 v41, v64, v41
	v_cndmask_b32_e64 v36, v36, v38, s[38:39]
	v_cndmask_b32_e64 v37, v37, v39, s[38:39]
	global_store_dwordx2 v[58:59], v[34:35], off offset:1536
	s_waitcnt lgkmcnt(1)
	v_add_f32_e32 v36, v36, v40
	s_waitcnt lgkmcnt(0)
	v_add_f32_e32 v37, v37, v41
	v_cndmask_b32_e64 v38, v36, v37, s[40:41]
	ds_bpermute_b32 v38, v65, v38
	v_cndmask_b32_e64 v36, v37, v36, s[40:41]
	s_waitcnt lgkmcnt(0)
	v_add_f32_e32 v36, v36, v38
	ds_bpermute_b32 v37, v66, v36
	s_waitcnt lgkmcnt(0)
	v_add_f32_e32 v36, v36, v37
	ds_bpermute_b32 v37, v67, v36
	s_and_saveexec_b64 s[0:1], s[42:43]
	s_cbranch_execz .LBB0_752
	v_lshl_add_u64 v[34:35], s[74:75], 0, v[56:57]
	s_waitcnt lgkmcnt(0)
	v_add_f32_e32 v36, v36, v37
	global_store_dword v[34:35], v36, off
	s_branch .LBB0_752
